# no priority raise in the MFMA blocks that carry an interleaved epilogue stream (GU and QKV/BIN/BGRP LAST block 4, FIRST_epi block 1)
# baseline (speedup 1.0000x reference)
; __device__ __forceinline__ unsigned cvt_pk_bf16(float lo, float hi) { unsigned r; asm volatile("v_cvt_pk_bf16_f32 %0, %1, %2" : "=v"(r) : "v"(lo), "v"(hi)); return r; }
; __device__ __forceinline__ float siluf_(float x) { return x * sigmoidf_(x); }
; #define PG8_STAGE(bufoff, gbase, voff) do { _Pragma("unroll") for (int _i = 0; _i < 2; ++_i) \
;         __builtin_amdgcn_global_load_lds((const unsigned*)((const char*)(gbase) + (voff)[_i]), (LAS unsigned*)(lds + (bufoff) + ldsw + _i * 8192), 16, 0, 0); } while (0)
; #define PG8_LDA(dst, b, h) do { _Pragma("unroll") for (int m = 0; m < 4; ++m) _Pragma("unroll") for (int k = 0; k < 2; ++k) dst[m][k] = *(const LAS bf16x8*)(lds + PG8_SA(b, h) + aoff + m * 2048 + k * 1024); } while (0)
; #define PG8_LDB(dst, b, h) do { _Pragma("unroll") for (int n = 0; n < 2; ++n) _Pragma("unroll") for (int k = 0; k < 2; ++k) dst[n][k] = *(const LAS bf16x8*)(lds + PG8_SB(b, h) + boff + n * 2048 + k * 1024); } while (0)
; #define PG8_WAIT_V(n) asm volatile("s_waitcnt vmcnt(" #n ")" ::: "memory")
; #define PG8_WAIT_L(n) asm volatile("s_waitcnt lgkmcnt(" #n ")" ::: "memory")
; #define PG8_BAR __builtin_amdgcn_s_barrier()
; #define PG8_SCHED __builtin_amdgcn_sched_barrier(0)
;     __device__ __forceinline__ void operator()(const f32x4 (&acc)[2][2][4][2], const Unit& u, int wr, int wc, int fr, int fq) const {
;     ...
;             for (int m = 0; m < 4; ++m) { const int row = row0 + ai * HALF + m * 16; bf16_t* rowp = O + (size_t)row * ldc + col0; const float rs = rsv[ai][m];
;                 f32x4 v0, v1;
; #pragma unroll
;                 for (int j = 0; j < 4; ++j) { v0[j] = siluf_(acc[ai][0][m][0][j] * rs) * (acc[ai][1][m][0][j] * rs); v1[j] = siluf_(acc[ai][0][m][1][j] * rs) * (acc[ai][1][m][1][j] * rs); }
;                 u32x4 w; w.x = cvt_pk_bf16(v0[0], v0[1]); w.y = cvt_pk_bf16(v0[2], v0[3]); w.z = cvt_pk_bf16(v1[0], v1[1]); w.w = cvt_pk_bf16(v1[2], v1[3]);
;                 *(u32x4*)rowp = w; }
; template <class Epi, bool ALIGN_EPI>
; __device__ __forceinline__ void gemm_phase(LAS unsigned char* lds, const Gemm g, const StaticOrder& S, const Epi& E, const int tid) {
;     ...
;             PG8_LDB(B0, 0, 0); PG8_LDB(B1, 0, 1); PG8_SCHED; PG8_LDA(At, 0, 0); PG8_STAGE(PG8_SA(1, 1), a1 + hA, voffA);
;             PG8_WAIT_V(8); PG8_WAIT_L(0); PG8_BAR; PG8_MMA(0, 0, At, B0); PG8_MMA(0, 1, At, B1); PG8_BAR; PG8_SCHED;
.Lgu_first_epi:
	s_add_i32 s11, s10, 2
	s_cmp_eq_u32 s58, s10
	v_lshl_add_u64 v[146:147], v[142:143], 0, s[92:93]
	s_cselect_b64 vcc, -1, 0
	v_add_u32_e32 v150, s33, v151
	s_add_i32 s10, 0, 0x14000
	v_cndmask_b32_e32 v167, v147, v139, vcc
	v_cndmask_b32_e32 v166, v146, v138, vcc
	ds_read_b128 v[146:149], v150
	ds_read_b128 v[154:157], v150 offset:1024
	ds_read_b128 v[158:161], v150 offset:2048
	ds_read_b128 v[162:165], v150 offset:3072
	v_add_u32_e32 v150, s10, v151
	ds_read_b128 v[176:179], v150
	ds_read_b128 v[180:183], v150 offset:1024
	ds_read_b128 v[184:187], v150 offset:2048
	ds_read_b128 v[188:191], v150 offset:3072
	v_cndmask_b32_e32 v221, v145, v141, vcc
	v_cndmask_b32_e32 v220, v144, v140, vcc
	v_lshl_add_u64 v[226:227], v[142:143], 0, v[134:135]
	s_add_i32 m0, s51, 0xc000
	ds_read_b128 v[192:195], v153
	ds_read_b128 v[196:199], v153 offset:1024
	ds_read_b128 v[200:203], v153 offset:2048
	ds_read_b128 v[204:207], v153 offset:3072
	ds_read_b128 v[208:211], v153 offset:4096
	ds_read_b128 v[212:215], v153 offset:5120
	ds_read_b128 v[216:219], v153 offset:6144
	ds_read_b128 v[240:243], v153 offset:7168
	global_load_lds_dwordx4 v[226:227], off
	v_lshl_add_u64 v[226:227], v[142:143], 0, v[136:137]
	s_add_i32 m0, s51, 0xe000
	s_nop 0
	global_load_lds_dwordx4 v[226:227], off
	s_waitcnt vmcnt(12)
	s_waitcnt lgkmcnt(0)
	s_barrier
	s_waitcnt lgkmcnt(0)
	v_mfma_f32_16x16x32_bf16 v[120:123], v[146:149], v[192:195], 0
	s_lshl_b32 s98, s28, 5
	s_mov_b32 s99, 0
	s_mov_b32 s100, 0xbfb8aa3b
	s_mov_b32 s101, 0xbfb8aa3b
	v_mul_f32_e32 v56, v238, v56
	v_mul_f32_e32 v57, v238, v57
	v_mul_f32_e32 v58, v238, v58
	v_mul_f32_e32 v59, v238, v59
	v_mul_f32_e32 v60, v238, v60
	v_mul_f32_e32 v61, v238, v61
	v_mfma_f32_16x16x32_bf16 v[112:115], v[158:161], v[192:195], 0
	v_mul_f32_e32 v62, v238, v62
	v_mul_f32_e32 v63, v238, v63
	v_mul_f32_e32 v224, s100, v56
	v_mul_f32_e32 v225, s101, v57
	v_mul_f32_e32 v228, s100, v58
	v_mul_f32_e32 v229, s101, v59
	v_exp_f32_e32 v224, v224
	v_exp_f32_e32 v225, v225
	v_exp_f32_e32 v228, v228
	v_exp_f32_e32 v229, v229
	v_mfma_f32_16x16x32_bf16 v[104:107], v[146:149], v[200:203], 0
	v_add_f32_e32 v224, 1.0, v224
	v_add_f32_e32 v225, 1.0, v225
	v_add_f32_e32 v228, 1.0, v228
	v_add_f32_e32 v229, 1.0, v229
	v_rcp_f32_e32 v224, v224
	v_rcp_f32_e32 v225, v225
	v_rcp_f32_e32 v228, v228
	v_rcp_f32_e32 v229, v229
	v_nop
	v_mul_f32_e32 v56, v224, v56
	v_mfma_f32_16x16x32_bf16 v[96:99], v[158:161], v[200:203], 0
	v_mul_f32_e32 v57, v225, v57
	v_mul_f32_e32 v58, v228, v58
	v_mul_f32_e32 v59, v229, v59
	v_mul_f32_e32 v56, v60, v56
	v_mul_f32_e32 v57, v61, v57
	v_mul_f32_e32 v58, v62, v58
	v_mul_f32_e32 v59, v63, v59
	v_mul_f32_e32 v48, v238, v48
	v_mul_f32_e32 v49, v238, v49
	v_mul_f32_e32 v50, v238, v50
	v_mfma_f32_16x16x32_bf16 v[88:91], v[146:149], v[208:211], 0
	v_mul_f32_e32 v51, v238, v51
	v_mul_f32_e32 v52, v238, v52
	v_mul_f32_e32 v53, v238, v53
	v_mul_f32_e32 v54, v238, v54
	v_mul_f32_e32 v55, v238, v55
	v_mul_f32_e32 v224, s100, v48
	v_mul_f32_e32 v225, s101, v49
	v_mul_f32_e32 v228, s100, v50
	v_mul_f32_e32 v229, s101, v51
	v_exp_f32_e32 v224, v224
	v_mfma_f32_16x16x32_bf16 v[80:83], v[158:161], v[208:211], 0
	v_exp_f32_e32 v225, v225
	v_exp_f32_e32 v228, v228
	v_exp_f32_e32 v229, v229
	v_add_f32_e32 v224, 1.0, v224
	v_add_f32_e32 v225, 1.0, v225
	v_add_f32_e32 v228, 1.0, v228
	v_add_f32_e32 v229, 1.0, v229
	v_rcp_f32_e32 v224, v224
	v_rcp_f32_e32 v225, v225
	v_rcp_f32_e32 v228, v228
	v_mfma_f32_16x16x32_bf16 v[72:75], v[146:149], v[216:219], 0
	v_rcp_f32_e32 v229, v229
	v_nop
	v_mul_f32_e32 v48, v224, v48
	v_mul_f32_e32 v49, v225, v49
	v_mul_f32_e32 v50, v228, v50
	v_mul_f32_e32 v51, v229, v51
	v_mul_f32_e32 v48, v52, v48
	v_mul_f32_e32 v49, v53, v49
	v_mul_f32_e32 v50, v54, v50
	v_mul_f32_e32 v51, v55, v51
	v_mfma_f32_16x16x32_bf16 v[64:67], v[158:161], v[216:219], 0
	v_cvt_pk_bf16_f32 v56, v56, v57
	v_cvt_pk_bf16_f32 v57, v58, v59
	v_cvt_pk_bf16_f32 v58, v48, v49
	v_cvt_pk_bf16_f32 v59, v50, v51
	global_store_dwordx4 v[232:233], v[56:59], off
	v_lshl_add_u64 v[232:233], v[232:233], 0, s[98:99]
	v_mul_f32_e32 v40, v239, v40
	v_mul_f32_e32 v41, v239, v41
	v_mul_f32_e32 v42, v239, v42
	v_mul_f32_e32 v43, v239, v43
	v_mfma_f32_16x16x32_bf16 v[120:123], v[154:157], v[196:199], v[120:123]
	v_mul_f32_e32 v44, v239, v44
	v_mul_f32_e32 v45, v239, v45
	v_mul_f32_e32 v46, v239, v46
	v_mul_f32_e32 v47, v239, v47
	v_mul_f32_e32 v224, s100, v40
	v_mul_f32_e32 v225, s101, v41
	v_mul_f32_e32 v228, s100, v42
	v_mul_f32_e32 v229, s101, v43
	v_exp_f32_e32 v224, v224
	v_exp_f32_e32 v225, v225
	v_mfma_f32_16x16x32_bf16 v[112:115], v[162:165], v[196:199], v[112:115]
	v_exp_f32_e32 v228, v228
	v_exp_f32_e32 v229, v229
	v_add_f32_e32 v224, 1.0, v224
	v_add_f32_e32 v225, 1.0, v225
	v_add_f32_e32 v228, 1.0, v228
	v_add_f32_e32 v229, 1.0, v229
	v_rcp_f32_e32 v224, v224
	v_rcp_f32_e32 v225, v225
	v_rcp_f32_e32 v228, v228
	v_rcp_f32_e32 v229, v229
	v_mfma_f32_16x16x32_bf16 v[104:107], v[154:157], v[204:207], v[104:107]
	v_nop
	v_mul_f32_e32 v40, v224, v40
	v_mul_f32_e32 v41, v225, v41
	v_mul_f32_e32 v42, v228, v42
	v_mul_f32_e32 v43, v229, v43
	v_mul_f32_e32 v40, v44, v40
	v_mul_f32_e32 v41, v45, v41
	v_mul_f32_e32 v42, v46, v42
	v_mul_f32_e32 v43, v47, v43
	v_mul_f32_e32 v32, v239, v32
	v_mfma_f32_16x16x32_bf16 v[96:99], v[162:165], v[204:207], v[96:99]
	v_mul_f32_e32 v33, v239, v33
	v_mul_f32_e32 v34, v239, v34
	v_mul_f32_e32 v35, v239, v35
	v_mul_f32_e32 v36, v239, v36
	v_mul_f32_e32 v37, v239, v37
	v_mul_f32_e32 v38, v239, v38
	v_mul_f32_e32 v39, v239, v39
	v_mul_f32_e32 v224, s100, v32
	v_mul_f32_e32 v225, s101, v33
	v_mul_f32_e32 v228, s100, v34
; __device__ __forceinline__ unsigned cvt_pk_bf16(float lo, float hi) { unsigned r; asm volatile("v_cvt_pk_bf16_f32 %0, %1, %2" : "=v"(r) : "v"(lo), "v"(hi)); return r; }
; __device__ __forceinline__ float siluf_(float x) { return x * sigmoidf_(x); }
; #define PG8_STAGE(bufoff, gbase, voff) do { _Pragma("unroll") for (int _i = 0; _i < 2; ++_i) \
;         __builtin_amdgcn_global_load_lds((const unsigned*)((const char*)(gbase) + (voff)[_i]), (LAS unsigned*)(lds + (bufoff) + ldsw + _i * 8192), 16, 0, 0); } while (0)
; #define PG8_LDA(dst, b, h) do { _Pragma("unroll") for (int m = 0; m < 4; ++m) _Pragma("unroll") for (int k = 0; k < 2; ++k) dst[m][k] = *(const LAS bf16x8*)(lds + PG8_SA(b, h) + aoff + m * 2048 + k * 1024); } while (0)
; #define PG8_LDB(dst, b, h) do { _Pragma("unroll") for (int n = 0; n < 2; ++n) _Pragma("unroll") for (int k = 0; k < 2; ++k) dst[n][k] = *(const LAS bf16x8*)(lds + PG8_SB(b, h) + boff + n * 2048 + k * 1024); } while (0)
; #define PG8_WAIT_V(n) asm volatile("s_waitcnt vmcnt(" #n ")" ::: "memory")
; #define PG8_WAIT_L(n) asm volatile("s_waitcnt lgkmcnt(" #n ")" ::: "memory")
; #define PG8_BAR __builtin_amdgcn_s_barrier()
; #define PG8_SCHED __builtin_amdgcn_sched_barrier(0)
;     __device__ __forceinline__ void operator()(const f32x4 (&acc)[2][2][4][2], const Unit& u, int wr, int wc, int fr, int fq) const {
;     ...
;             for (int m = 0; m < 4; ++m) { const int row = row0 + ai * HALF + m * 16; bf16_t* rowp = O + (size_t)row * ldc + col0; const float rs = rsv[ai][m];
;                 f32x4 v0, v1;
; #pragma unroll
;                 for (int j = 0; j < 4; ++j) { v0[j] = siluf_(acc[ai][0][m][0][j] * rs) * (acc[ai][1][m][0][j] * rs); v1[j] = siluf_(acc[ai][0][m][1][j] * rs) * (acc[ai][1][m][1][j] * rs); }
;                 u32x4 w; w.x = cvt_pk_bf16(v0[0], v0[1]); w.y = cvt_pk_bf16(v0[2], v0[3]); w.z = cvt_pk_bf16(v1[0], v1[1]); w.w = cvt_pk_bf16(v1[2], v1[3]);
;                 *(u32x4*)rowp = w; }
; template <class Epi, bool ALIGN_EPI>
; __device__ __forceinline__ void gemm_phase(LAS unsigned char* lds, const Gemm g, const StaticOrder& S, const Epi& E, const int tid) {
;     ...
;             PG8_LDB(B0, 0, 0); PG8_LDB(B1, 0, 1); PG8_SCHED; PG8_LDA(At, 0, 0); PG8_STAGE(PG8_SA(1, 1), a1 + hA, voffA);
;             PG8_WAIT_V(8); PG8_WAIT_L(0); PG8_BAR; PG8_MMA(0, 0, At, B0); PG8_MMA(0, 1, At, B1); PG8_BAR; PG8_SCHED;
	v_mfma_f32_16x16x32_bf16 v[88:91], v[154:157], v[212:215], v[88:91]
	v_mul_f32_e32 v229, s101, v35
	v_exp_f32_e32 v224, v224
	v_exp_f32_e32 v225, v225
	v_exp_f32_e32 v228, v228
	v_exp_f32_e32 v229, v229
	v_add_f32_e32 v224, 1.0, v224
	v_add_f32_e32 v225, 1.0, v225
	v_add_f32_e32 v228, 1.0, v228
	v_add_f32_e32 v229, 1.0, v229
	v_rcp_f32_e32 v224, v224
	v_mfma_f32_16x16x32_bf16 v[80:83], v[162:165], v[212:215], v[80:83]
	v_rcp_f32_e32 v225, v225
	v_rcp_f32_e32 v228, v228
	v_rcp_f32_e32 v229, v229
	v_nop
	v_mul_f32_e32 v32, v224, v32
	v_mul_f32_e32 v33, v225, v33
	v_mul_f32_e32 v34, v228, v34
	v_mul_f32_e32 v35, v229, v35
	v_mul_f32_e32 v32, v36, v32
	v_mul_f32_e32 v33, v37, v33
	v_mfma_f32_16x16x32_bf16 v[72:75], v[154:157], v[240:243], v[72:75]
	v_mul_f32_e32 v34, v38, v34
	v_mul_f32_e32 v35, v39, v35
	v_cvt_pk_bf16_f32 v40, v40, v41
	v_cvt_pk_bf16_f32 v41, v42, v43
	v_cvt_pk_bf16_f32 v42, v32, v33
	v_cvt_pk_bf16_f32 v43, v34, v35
	global_store_dwordx4 v[232:233], v[40:43], off
	v_lshl_add_u64 v[232:233], v[232:233], 0, s[98:99]
	v_mul_f32_e32 v24, v230, v24
	v_mul_f32_e32 v25, v230, v25
	v_mfma_f32_16x16x32_bf16 v[64:67], v[162:165], v[240:243], v[64:67]
	v_mul_f32_e32 v26, v230, v26
	v_mul_f32_e32 v27, v230, v27
	v_mul_f32_e32 v28, v230, v28
	v_mul_f32_e32 v29, v230, v29
	v_mul_f32_e32 v30, v230, v30
	v_mul_f32_e32 v31, v230, v31
	v_mul_f32_e32 v224, s100, v24
	v_mul_f32_e32 v225, s101, v25
	v_mul_f32_e32 v228, s100, v26
	v_mul_f32_e32 v229, s101, v27
	s_setprio 0
	v_mfma_f32_16x16x32_bf16 v[124:127], v[176:179], v[192:195], 0
	v_exp_f32_e32 v224, v224
	v_exp_f32_e32 v225, v225
	v_exp_f32_e32 v228, v228
	v_exp_f32_e32 v229, v229
	v_add_f32_e32 v224, 1.0, v224
	v_add_f32_e32 v225, 1.0, v225
	v_add_f32_e32 v228, 1.0, v228
	v_add_f32_e32 v229, 1.0, v229
	v_rcp_f32_e32 v224, v224
	v_rcp_f32_e32 v225, v225
	v_mfma_f32_16x16x32_bf16 v[116:119], v[184:187], v[192:195], 0
	v_rcp_f32_e32 v228, v228
	v_rcp_f32_e32 v229, v229
	v_nop
	v_mul_f32_e32 v24, v224, v24
	v_mul_f32_e32 v25, v225, v25
	v_mul_f32_e32 v26, v228, v26
	v_mul_f32_e32 v27, v229, v27
	v_mul_f32_e32 v24, v28, v24
	v_mul_f32_e32 v25, v29, v25
	v_mul_f32_e32 v26, v30, v26
	v_mfma_f32_16x16x32_bf16 v[108:111], v[176:179], v[200:203], 0
	v_mul_f32_e32 v27, v31, v27
	v_mul_f32_e32 v16, v230, v16
	v_mul_f32_e32 v17, v230, v17
	v_mul_f32_e32 v18, v230, v18
	v_mul_f32_e32 v19, v230, v19
	v_mul_f32_e32 v20, v230, v20
	v_mul_f32_e32 v21, v230, v21
	v_mul_f32_e32 v22, v230, v22
	v_mul_f32_e32 v23, v230, v23
	v_mul_f32_e32 v224, s100, v16
	v_mfma_f32_16x16x32_bf16 v[100:103], v[184:187], v[200:203], 0
	v_mul_f32_e32 v225, s101, v17
	v_mul_f32_e32 v228, s100, v18
	v_mul_f32_e32 v229, s101, v19
	v_exp_f32_e32 v224, v224
	v_exp_f32_e32 v225, v225
	v_exp_f32_e32 v228, v228
	v_exp_f32_e32 v229, v229
	v_add_f32_e32 v224, 1.0, v224
	v_add_f32_e32 v225, 1.0, v225
	v_add_f32_e32 v228, 1.0, v228
	v_mfma_f32_16x16x32_bf16 v[92:95], v[176:179], v[208:211], 0
	v_add_f32_e32 v229, 1.0, v229
	v_rcp_f32_e32 v224, v224
	v_rcp_f32_e32 v225, v225
	v_rcp_f32_e32 v228, v228
	v_rcp_f32_e32 v229, v229
	v_nop
	v_mul_f32_e32 v16, v224, v16
	v_mul_f32_e32 v17, v225, v17
	v_mul_f32_e32 v18, v228, v18
	v_mul_f32_e32 v19, v229, v19
	v_mfma_f32_16x16x32_bf16 v[84:87], v[184:187], v[208:211], 0
	v_mul_f32_e32 v16, v20, v16
	v_mul_f32_e32 v17, v21, v17
	v_mul_f32_e32 v18, v22, v18
	v_mul_f32_e32 v19, v23, v19
	v_cvt_pk_bf16_f32 v24, v24, v25
	v_cvt_pk_bf16_f32 v25, v26, v27
	v_cvt_pk_bf16_f32 v26, v16, v17
	v_cvt_pk_bf16_f32 v27, v18, v19
	global_store_dwordx4 v[232:233], v[24:27], off
	v_lshl_add_u64 v[232:233], v[232:233], 0, s[98:99]
	v_mfma_f32_16x16x32_bf16 v[76:79], v[176:179], v[216:219], 0
	v_mul_f32_e32 v8, v231, v8
	v_mul_f32_e32 v9, v231, v9
	v_mul_f32_e32 v10, v231, v10
	v_mul_f32_e32 v11, v231, v11
	v_mul_f32_e32 v12, v231, v12
	v_mul_f32_e32 v13, v231, v13
	v_mul_f32_e32 v14, v231, v14
	v_mul_f32_e32 v15, v231, v15
	v_mul_f32_e32 v224, s100, v8
	v_mul_f32_e32 v225, s101, v9
	v_mfma_f32_16x16x32_bf16 v[68:71], v[184:187], v[216:219], 0
	v_mul_f32_e32 v228, s100, v10
	v_mul_f32_e32 v229, s101, v11
	v_exp_f32_e32 v224, v224
	v_exp_f32_e32 v225, v225
	v_exp_f32_e32 v228, v228
	v_exp_f32_e32 v229, v229
	v_add_f32_e32 v224, 1.0, v224
	v_add_f32_e32 v225, 1.0, v225
	v_add_f32_e32 v228, 1.0, v228
	v_add_f32_e32 v229, 1.0, v229
	v_mfma_f32_16x16x32_bf16 v[124:127], v[180:183], v[196:199], v[124:127]
	v_rcp_f32_e32 v224, v224
	v_rcp_f32_e32 v225, v225
	v_rcp_f32_e32 v228, v228
	v_rcp_f32_e32 v229, v229
	v_nop
	v_mul_f32_e32 v8, v224, v8
	v_mul_f32_e32 v9, v225, v9
	v_mul_f32_e32 v10, v228, v10
	v_mul_f32_e32 v11, v229, v11
	v_mul_f32_e32 v8, v12, v8
	v_mfma_f32_16x16x32_bf16 v[116:119], v[188:191], v[196:199], v[116:119]
	v_mul_f32_e32 v9, v13, v9
	v_mul_f32_e32 v10, v14, v10
	v_mul_f32_e32 v11, v15, v11
	v_mul_f32_e32 v4, v231, v4
	v_mul_f32_e32 v5, v231, v5
	v_mul_f32_e32 v6, v231, v6
	v_mul_f32_e32 v7, v231, v7
	v_mul_f32_e32 v0, v231, v0
	v_mul_f32_e32 v1, v231, v1
	v_mul_f32_e32 v2, v231, v2
	v_mfma_f32_16x16x32_bf16 v[108:111], v[180:183], v[204:207], v[108:111]
	v_mul_f32_e32 v3, v231, v3
	v_mul_f32_e32 v224, s100, v4
	v_mul_f32_e32 v225, s101, v5
	v_mul_f32_e32 v228, s100, v6
	v_mul_f32_e32 v229, s101, v7
	v_exp_f32_e32 v224, v224
	v_exp_f32_e32 v225, v225
	v_exp_f32_e32 v228, v228
	v_exp_f32_e32 v229, v229
	v_add_f32_e32 v224, 1.0, v224
	v_mfma_f32_16x16x32_bf16 v[100:103], v[188:191], v[204:207], v[100:103]
	v_add_f32_e32 v225, 1.0, v225
	v_add_f32_e32 v228, 1.0, v228
	v_add_f32_e32 v229, 1.0, v229
	v_rcp_f32_e32 v224, v224
	v_rcp_f32_e32 v225, v225
	v_rcp_f32_e32 v228, v228
	v_rcp_f32_e32 v229, v229
	v_nop
	v_mul_f32_e32 v4, v224, v4
	v_mul_f32_e32 v5, v225, v5
	v_mfma_f32_16x16x32_bf16 v[92:95], v[180:183], v[212:215], v[92:95]
	v_mul_f32_e32 v6, v228, v6
	v_mul_f32_e32 v7, v229, v7
	v_mul_f32_e32 v4, v0, v4
	v_mul_f32_e32 v5, v1, v5
	v_mul_f32_e32 v6, v2, v6
	v_mul_f32_e32 v7, v3, v7
	v_cvt_pk_bf16_f32 v8, v8, v9
	v_cvt_pk_bf16_f32 v9, v10, v11
	v_cvt_pk_bf16_f32 v10, v4, v5
	v_cvt_pk_bf16_f32 v11, v6, v7
	v_mfma_f32_16x16x32_bf16 v[84:87], v[188:191], v[212:215], v[84:87]
	global_store_dwordx4 v[232:233], v[8:11], off
	v_mfma_f32_16x16x32_bf16 v[76:79], v[180:183], v[240:243], v[76:79]
	v_mfma_f32_16x16x32_bf16 v[68:71], v[188:191], v[240:243], v[68:71]
	s_setprio 0
	s_barrier
; #define PG8_STAGE(bufoff, gbase, voff) do { _Pragma("unroll") for (int _i = 0; _i < 2; ++_i) \
;         __builtin_amdgcn_global_load_lds((const unsigned*)((const char*)(gbase) + (voff)[_i]), (LAS unsigned*)(lds + (bufoff) + ldsw + _i * 8192), 16, 0, 0); } while (0)
; #define PG8_LDA(dst, b, h) do { _Pragma("unroll") for (int m = 0; m < 4; ++m) _Pragma("unroll") for (int k = 0; k < 2; ++k) dst[m][k] = *(const LAS bf16x8*)(lds + PG8_SA(b, h) + aoff + m * 2048 + k * 1024); } while (0)
; #define PG8_LDB(dst, b, h) do { _Pragma("unroll") for (int n = 0; n < 2; ++n) _Pragma("unroll") for (int k = 0; k < 2; ++k) dst[n][k] = *(const LAS bf16x8*)(lds + PG8_SB(b, h) + boff + n * 2048 + k * 1024); } while (0)
; #define PG8_MMA(ai, bj, At, Bt) do { __builtin_amdgcn_s_setprio(1); _Pragma("unroll") for (int k = 0; k < 2; ++k) _Pragma("unroll") for (int m = 0; m < 4; ++m) _Pragma("unroll") for (int n = 0; n < 2; ++n) \
;         acc[ai][bj][m][n] = __builtin_amdgcn_mfma_f32_16x16x32_bf16(Bt[n][k], At[m][k], acc[ai][bj][m][n], 0, 0, 0); __builtin_amdgcn_s_setprio(0); } while (0)
; #define PG8_WAIT_V(n) asm volatile("s_waitcnt vmcnt(" #n ")" ::: "memory")
; #define PG8_WAIT_L(n) asm volatile("s_waitcnt lgkmcnt(" #n ")" ::: "memory")
; #define PG8_BAR __builtin_amdgcn_s_barrier()
; #define PG8_SCHED __builtin_amdgcn_sched_barrier(0)
; template <class Epi, bool ALIGN_EPI>
; __device__ __forceinline__ void gemm_phase(LAS unsigned char* lds, const Gemm g, const StaticOrder& S, const Epi& E, const int tid) {
;     ...
;             PG8_LDA(At, 0, 1); PG8_STAGE(PG8_SB(0, 0), b2, voffB); PG8_STAGE(PG8_SB(0, 1), b2 + hB, voffB); PG8_STAGE(PG8_SA(0, 0), a2, voffA);
;             PG8_WAIT_V(8); PG8_WAIT_L(0); PG8_BAR; PG8_MMA(1, 0, At, B0); PG8_MMA(1, 1, At, B1); PG8_BAR; PG8_SCHED;
;             PG8_LDB(B0, 1, 0); PG8_LDB(B1, 1, 1); PG8_SCHED; PG8_LDA(At, 1, 0); PG8_STAGE(PG8_SA(0, 1), a2 + hA, voffA);
;             PG8_WAIT_V(8); PG8_WAIT_L(0); PG8_BAR; PG8_MMA(0, 0, At, B0); PG8_MMA(0, 1, At, B1); PG8_BAR; PG8_SCHED;
	s_add_i32 s65, s33, s45
	v_lshl_add_u64 v[226:227], v[220:221], 0, v[168:169]
	s_mov_b32 m0, s65
	ds_read_b128 v[192:195], v153 offset:16384
	ds_read_b128 v[196:199], v153 offset:17408
	ds_read_b128 v[200:203], v153 offset:18432
	ds_read_b128 v[204:207], v153 offset:19456
	ds_read_b128 v[208:211], v153 offset:20480
	ds_read_b128 v[212:215], v153 offset:21504
	ds_read_b128 v[216:219], v153 offset:22528
	ds_read_b128 v[240:243], v153 offset:23552
	global_load_lds_dwordx4 v[226:227], off
	v_lshl_add_u64 v[244:245], v[220:221], 0, v[128:129]
	s_add_i32 m0, s65, 0x2000
	v_lshl_add_u64 v[220:221], v[220:221], 0, s[12:13]
	s_add_i32 s10, s10, s45
	global_load_lds_dwordx4 v[244:245], off
	v_lshl_add_u64 v[246:247], v[220:221], 0, v[168:169]
	s_mov_b32 m0, s10
	v_lshl_add_u64 v[220:221], v[220:221], 0, v[128:129]
	global_load_lds_dwordx4 v[246:247], off
	s_add_i32 m0, s10, 0x2000
	v_lshl_add_u64 v[248:249], v[166:167], 0, v[132:133]
	global_load_lds_dwordx4 v[220:221], off
	s_mov_b32 m0, s51
	v_lshl_add_u64 v[250:251], v[166:167], 0, v[130:131]
	global_load_lds_dwordx4 v[248:249], off
	s_mov_b32 m0, s52
	s_nop 0
	global_load_lds_dwordx4 v[250:251], off
	s_waitcnt vmcnt(16)
	s_waitcnt lgkmcnt(0)
	s_barrier
	s_setprio 1
	s_waitcnt lgkmcnt(0)
	v_mfma_f32_16x16x32_bf16 v[56:59], v[146:149], v[192:195], 0
	v_mfma_f32_16x16x32_bf16 v[48:51], v[158:161], v[192:195], 0
	v_mfma_f32_16x16x32_bf16 v[40:43], v[146:149], v[200:203], 0
	v_mfma_f32_16x16x32_bf16 v[32:35], v[158:161], v[200:203], 0
	v_mfma_f32_16x16x32_bf16 v[24:27], v[146:149], v[208:211], 0
	v_mfma_f32_16x16x32_bf16 v[16:19], v[158:161], v[208:211], 0
	v_mfma_f32_16x16x32_bf16 v[8:11], v[146:149], v[216:219], 0
	v_mfma_f32_16x16x32_bf16 v[4:7], v[158:161], v[216:219], 0
	v_mfma_f32_16x16x32_bf16 v[56:59], v[154:157], v[196:199], v[56:59]
	v_mfma_f32_16x16x32_bf16 v[48:51], v[162:165], v[196:199], v[48:51]
	v_mfma_f32_16x16x32_bf16 v[40:43], v[154:157], v[204:207], v[40:43]
	v_mfma_f32_16x16x32_bf16 v[32:35], v[162:165], v[204:207], v[32:35]
	v_mfma_f32_16x16x32_bf16 v[24:27], v[154:157], v[212:215], v[24:27]
	v_mfma_f32_16x16x32_bf16 v[16:19], v[162:165], v[212:215], v[16:19]
	v_mfma_f32_16x16x32_bf16 v[8:11], v[154:157], v[240:243], v[8:11]
	v_mfma_f32_16x16x32_bf16 v[4:7], v[162:165], v[240:243], v[4:7]
	s_setprio 0
	s_setprio 1
	v_mfma_f32_16x16x32_bf16 v[60:63], v[176:179], v[192:195], 0
	v_mfma_f32_16x16x32_bf16 v[52:55], v[184:187], v[192:195], 0
	v_mfma_f32_16x16x32_bf16 v[44:47], v[176:179], v[200:203], 0
	v_mfma_f32_16x16x32_bf16 v[36:39], v[184:187], v[200:203], 0
	v_mfma_f32_16x16x32_bf16 v[28:31], v[176:179], v[208:211], 0
	v_mfma_f32_16x16x32_bf16 v[20:23], v[184:187], v[208:211], 0
	v_mfma_f32_16x16x32_bf16 v[12:15], v[176:179], v[216:219], 0
	v_mfma_f32_16x16x32_bf16 v[0:3], v[184:187], v[216:219], 0
	v_mfma_f32_16x16x32_bf16 v[60:63], v[180:183], v[196:199], v[60:63]
	v_mfma_f32_16x16x32_bf16 v[52:55], v[188:191], v[196:199], v[52:55]
	v_mfma_f32_16x16x32_bf16 v[44:47], v[180:183], v[204:207], v[44:47]
	v_mfma_f32_16x16x32_bf16 v[36:39], v[188:191], v[204:207], v[36:39]
	v_mfma_f32_16x16x32_bf16 v[28:31], v[180:183], v[212:215], v[28:31]
	v_mfma_f32_16x16x32_bf16 v[20:23], v[188:191], v[212:215], v[20:23]
	v_mfma_f32_16x16x32_bf16 v[12:15], v[180:183], v[240:243], v[12:15]
	v_mfma_f32_16x16x32_bf16 v[0:3], v[188:191], v[240:243], v[0:3]
	s_setprio 0
	s_barrier
	s_add_i32 s10, 0, 0x18000
	v_add_u32_e32 v150, s10, v151
	s_add_i32 s65, 0, 0x1c000
	ds_read_b128 v[146:149], v150
	ds_read_b128 v[154:157], v150 offset:1024
	ds_read_b128 v[158:161], v150 offset:2048
	ds_read_b128 v[162:165], v150 offset:3072
	v_add_u32_e32 v150, s65, v151
	ds_read_b128 v[176:179], v150
	ds_read_b128 v[180:183], v150 offset:1024
	ds_read_b128 v[184:187], v150 offset:2048
	ds_read_b128 v[188:191], v150 offset:3072
	v_lshl_add_u64 v[166:167], v[166:167], 0, s[94:95]
	s_mov_b32 m0, s53
	v_lshl_add_u64 v[252:253], v[166:167], 0, v[132:133]
	ds_read_b128 v[192:195], v153 offset:32768
	ds_read_b128 v[196:199], v153 offset:33792
	ds_read_b128 v[200:203], v153 offset:34816
	ds_read_b128 v[204:207], v153 offset:35840
	ds_read_b128 v[208:211], v153 offset:36864
	ds_read_b128 v[212:215], v153 offset:37888
	ds_read_b128 v[216:219], v153 offset:38912
	ds_read_b128 v[240:243], v153 offset:39936
	global_load_lds_dwordx4 v[252:253], off
	v_lshl_add_u64 v[166:167], v[166:167], 0, v[130:131]
	s_mov_b32 m0, s54
	s_nop 0
	global_load_lds_dwordx4 v[166:167], off
	s_waitcnt vmcnt(12)
	s_waitcnt lgkmcnt(0)
	s_barrier
; #define PG8_STAGE(bufoff, gbase, voff) do { _Pragma("unroll") for (int _i = 0; _i < 2; ++_i) \
;         __builtin_amdgcn_global_load_lds((const unsigned*)((const char*)(gbase) + (voff)[_i]), (LAS unsigned*)(lds + (bufoff) + ldsw + _i * 8192), 16, 0, 0); } while (0)
; #define PG8_LDA(dst, b, h) do { _Pragma("unroll") for (int m = 0; m < 4; ++m) _Pragma("unroll") for (int k = 0; k < 2; ++k) dst[m][k] = *(const LAS bf16x8*)(lds + PG8_SA(b, h) + aoff + m * 2048 + k * 1024); } while (0)
; #define PG8_MMA(ai, bj, At, Bt) do { __builtin_amdgcn_s_setprio(1); _Pragma("unroll") for (int k = 0; k < 2; ++k) _Pragma("unroll") for (int m = 0; m < 4; ++m) _Pragma("unroll") for (int n = 0; n < 2; ++n) \
;         acc[ai][bj][m][n] = __builtin_amdgcn_mfma_f32_16x16x32_bf16(Bt[n][k], At[m][k], acc[ai][bj][m][n], 0, 0, 0); __builtin_amdgcn_s_setprio(0); } while (0)
; #define PG8_WAIT_V(n) asm volatile("s_waitcnt vmcnt(" #n ")" ::: "memory")
; #define PG8_WAIT_L(n) asm volatile("s_waitcnt lgkmcnt(" #n ")" ::: "memory")
; #define PG8_BAR __builtin_amdgcn_s_barrier()
; #define PG8_SCHED __builtin_amdgcn_sched_barrier(0)
; template <class Epi, bool ALIGN_EPI>
; __device__ __forceinline__ void gemm_phase(LAS unsigned char* lds, const Gemm g, const StaticOrder& S, const Epi& E, const int tid) {
;     ...
;         for (int t = 0; t < nt; t += 2) {
;     ...
;             PG8_WAIT_V(8); PG8_WAIT_L(0); PG8_BAR; PG8_MMA(0, 0, At, B0); PG8_MMA(0, 1, At, B1); PG8_BAR; PG8_SCHED;
;             PG8_LDA(At, 1, 1); PG8_STAGE(PG8_SB(1, 0), b3, voffB); PG8_STAGE(PG8_SB(1, 1), b3 + hB, voffB); PG8_STAGE(PG8_SA(1, 0), a3, voffA);
;             PG8_WAIT_V(8); PG8_WAIT_L(0); PG8_BAR; PG8_MMA(1, 0, At, B0); PG8_MMA(1, 1, At, B1); PG8_BAR; PG8_SCHED;
;         }
	s_setprio 1
	s_waitcnt lgkmcnt(0)
	v_mfma_f32_16x16x32_bf16 v[120:123], v[146:149], v[192:195], v[120:123]
	v_mfma_f32_16x16x32_bf16 v[112:115], v[158:161], v[192:195], v[112:115]
	v_mfma_f32_16x16x32_bf16 v[104:107], v[146:149], v[200:203], v[104:107]
	v_mfma_f32_16x16x32_bf16 v[96:99], v[158:161], v[200:203], v[96:99]
	v_mfma_f32_16x16x32_bf16 v[88:91], v[146:149], v[208:211], v[88:91]
	v_mfma_f32_16x16x32_bf16 v[80:83], v[158:161], v[208:211], v[80:83]
	v_mfma_f32_16x16x32_bf16 v[72:75], v[146:149], v[216:219], v[72:75]
	v_mfma_f32_16x16x32_bf16 v[64:67], v[158:161], v[216:219], v[64:67]
	v_mfma_f32_16x16x32_bf16 v[120:123], v[154:157], v[196:199], v[120:123]
	v_mfma_f32_16x16x32_bf16 v[112:115], v[162:165], v[196:199], v[112:115]
	v_mfma_f32_16x16x32_bf16 v[104:107], v[154:157], v[204:207], v[104:107]
	v_mfma_f32_16x16x32_bf16 v[96:99], v[162:165], v[204:207], v[96:99]
	v_mfma_f32_16x16x32_bf16 v[88:91], v[154:157], v[212:215], v[88:91]
	v_mfma_f32_16x16x32_bf16 v[80:83], v[162:165], v[212:215], v[80:83]
	v_mfma_f32_16x16x32_bf16 v[72:75], v[154:157], v[240:243], v[72:75]
	v_mfma_f32_16x16x32_bf16 v[64:67], v[162:165], v[240:243], v[64:67]
	s_setprio 0
	s_setprio 1
	v_mfma_f32_16x16x32_bf16 v[124:127], v[176:179], v[192:195], v[124:127]
	v_mfma_f32_16x16x32_bf16 v[116:119], v[184:187], v[192:195], v[116:119]
	v_mfma_f32_16x16x32_bf16 v[108:111], v[176:179], v[200:203], v[108:111]
	v_mfma_f32_16x16x32_bf16 v[100:103], v[184:187], v[200:203], v[100:103]
	v_mfma_f32_16x16x32_bf16 v[92:95], v[176:179], v[208:211], v[92:95]
	v_mfma_f32_16x16x32_bf16 v[84:87], v[184:187], v[208:211], v[84:87]
	v_mfma_f32_16x16x32_bf16 v[76:79], v[176:179], v[216:219], v[76:79]
	v_mfma_f32_16x16x32_bf16 v[68:71], v[184:187], v[216:219], v[68:71]
	v_mfma_f32_16x16x32_bf16 v[124:127], v[180:183], v[196:199], v[124:127]
	v_mfma_f32_16x16x32_bf16 v[116:119], v[188:191], v[196:199], v[116:119]
	v_mfma_f32_16x16x32_bf16 v[108:111], v[180:183], v[204:207], v[108:111]
	v_mfma_f32_16x16x32_bf16 v[100:103], v[188:191], v[204:207], v[100:103]
	v_mfma_f32_16x16x32_bf16 v[92:95], v[180:183], v[212:215], v[92:95]
	v_mfma_f32_16x16x32_bf16 v[84:87], v[188:191], v[212:215], v[84:87]
	v_mfma_f32_16x16x32_bf16 v[76:79], v[180:183], v[240:243], v[76:79]
	v_mfma_f32_16x16x32_bf16 v[68:71], v[188:191], v[240:243], v[68:71]
	s_setprio 0
	s_barrier
	s_add_i32 s10, s10, s45
	v_lshl_add_u64 v[166:167], v[226:227], 0, s[92:93]
	s_mov_b32 m0, s10
	ds_read_b128 v[192:195], v153 offset:49152
	ds_read_b128 v[196:199], v153 offset:50176
	ds_read_b128 v[200:203], v153 offset:51200
	ds_read_b128 v[204:207], v153 offset:52224
	ds_read_b128 v[208:211], v153 offset:53248
	ds_read_b128 v[212:215], v153 offset:54272
	ds_read_b128 v[216:219], v153 offset:55296
	ds_read_b128 v[240:243], v153 offset:56320
	global_load_lds_dwordx4 v[166:167], off
	v_lshl_add_u64 v[166:167], v[244:245], 0, s[92:93]
	s_add_i32 m0, s10, 0x2000
	s_add_i32 s10, s65, s45
	global_load_lds_dwordx4 v[166:167], off
	v_lshl_add_u64 v[166:167], v[246:247], 0, s[92:93]
	s_mov_b32 m0, s10
	s_nop 0
	global_load_lds_dwordx4 v[166:167], off
	v_lshl_add_u64 v[166:167], v[220:221], 0, s[92:93]
	s_add_i32 m0, s10, 0x2000
	s_nop 0
	global_load_lds_dwordx4 v[166:167], off
	v_lshl_add_u64 v[166:167], v[248:249], 0, s[92:93]
	s_mov_b32 m0, s56
	s_nop 0
	global_load_lds_dwordx4 v[166:167], off
	v_lshl_add_u64 v[166:167], v[250:251], 0, s[92:93]
	s_mov_b32 m0, s57
	s_nop 0
	global_load_lds_dwordx4 v[166:167], off
	s_waitcnt vmcnt(8)
	s_waitcnt lgkmcnt(0)
	s_barrier
	s_setprio 1
	s_waitcnt lgkmcnt(0)
	v_mfma_f32_16x16x32_bf16 v[56:59], v[146:149], v[192:195], v[56:59]
	v_mfma_f32_16x16x32_bf16 v[48:51], v[158:161], v[192:195], v[48:51]
	v_mfma_f32_16x16x32_bf16 v[40:43], v[146:149], v[200:203], v[40:43]
	v_mfma_f32_16x16x32_bf16 v[32:35], v[158:161], v[200:203], v[32:35]
	v_mfma_f32_16x16x32_bf16 v[24:27], v[146:149], v[208:211], v[24:27]
	v_mfma_f32_16x16x32_bf16 v[16:19], v[158:161], v[208:211], v[16:19]
	v_mfma_f32_16x16x32_bf16 v[8:11], v[146:149], v[216:219], v[8:11]
	v_mfma_f32_16x16x32_bf16 v[4:7], v[158:161], v[216:219], v[4:7]
	v_mfma_f32_16x16x32_bf16 v[56:59], v[154:157], v[196:199], v[56:59]
	v_mfma_f32_16x16x32_bf16 v[48:51], v[162:165], v[196:199], v[48:51]
	v_mfma_f32_16x16x32_bf16 v[40:43], v[154:157], v[204:207], v[40:43]
	v_mfma_f32_16x16x32_bf16 v[32:35], v[162:165], v[204:207], v[32:35]
	v_mfma_f32_16x16x32_bf16 v[24:27], v[154:157], v[212:215], v[24:27]
	v_mfma_f32_16x16x32_bf16 v[16:19], v[162:165], v[212:215], v[16:19]
	v_mfma_f32_16x16x32_bf16 v[8:11], v[154:157], v[240:243], v[8:11]
	v_mfma_f32_16x16x32_bf16 v[4:7], v[162:165], v[240:243], v[4:7]
	s_setprio 0
	s_setprio 1
	v_mfma_f32_16x16x32_bf16 v[60:63], v[176:179], v[192:195], v[60:63]
	v_mfma_f32_16x16x32_bf16 v[52:55], v[184:187], v[192:195], v[52:55]
	v_mfma_f32_16x16x32_bf16 v[44:47], v[176:179], v[200:203], v[44:47]
	v_mfma_f32_16x16x32_bf16 v[36:39], v[184:187], v[200:203], v[36:39]
	v_mfma_f32_16x16x32_bf16 v[28:31], v[176:179], v[208:211], v[28:31]
	v_mfma_f32_16x16x32_bf16 v[20:23], v[184:187], v[208:211], v[20:23]
	v_mfma_f32_16x16x32_bf16 v[12:15], v[176:179], v[216:219], v[12:15]
	v_mfma_f32_16x16x32_bf16 v[0:3], v[184:187], v[216:219], v[0:3]
	v_mfma_f32_16x16x32_bf16 v[60:63], v[180:183], v[196:199], v[60:63]
	v_mfma_f32_16x16x32_bf16 v[52:55], v[188:191], v[196:199], v[52:55]
	v_mfma_f32_16x16x32_bf16 v[44:47], v[180:183], v[204:207], v[44:47]
	v_mfma_f32_16x16x32_bf16 v[36:39], v[188:191], v[204:207], v[36:39]
	v_mfma_f32_16x16x32_bf16 v[28:31], v[180:183], v[212:215], v[28:31]
	v_mfma_f32_16x16x32_bf16 v[20:23], v[188:191], v[212:215], v[20:23]
	v_mfma_f32_16x16x32_bf16 v[12:15], v[180:183], v[240:243], v[12:15]
	v_mfma_f32_16x16x32_bf16 v[0:3], v[188:191], v[240:243], v[0:3]
	s_setprio 0
	s_barrier
	v_lshl_add_u64 v[142:143], v[142:143], 0, s[80:81]
	v_lshl_add_u64 v[144:145], v[144:145], 0, s[80:81]
	s_mov_b32 s10, s11
	s_cmp_eq_u32 s10, s58
	s_cbranch_scc1 .Lgu_last
	s_branch .LBB0_308

; #define PG8_STAGE(bufoff, gbase, voff) do { _Pragma("unroll") for (int _i = 0; _i < 2; ++_i) \
;         __builtin_amdgcn_global_load_lds((const unsigned*)((const char*)(gbase) + (voff)[_i]), (LAS unsigned*)(lds + (bufoff) + ldsw + _i * 8192), 16, 0, 0); } while (0)
; #define PG8_LDA(dst, b, h) do { _Pragma("unroll") for (int m = 0; m < 4; ++m) _Pragma("unroll") for (int k = 0; k < 2; ++k) dst[m][k] = *(const LAS bf16x8*)(lds + PG8_SA(b, h) + aoff + m * 2048 + k * 1024); } while (0)
; #define PG8_LDB(dst, b, h) do { _Pragma("unroll") for (int n = 0; n < 2; ++n) _Pragma("unroll") for (int k = 0; k < 2; ++k) dst[n][k] = *(const LAS bf16x8*)(lds + PG8_SB(b, h) + boff + n * 2048 + k * 1024); } while (0)
; #define PG8_MMA(ai, bj, At, Bt) do { __builtin_amdgcn_s_setprio(1); _Pragma("unroll") for (int k = 0; k < 2; ++k) _Pragma("unroll") for (int m = 0; m < 4; ++m) _Pragma("unroll") for (int n = 0; n < 2; ++n) \
;         acc[ai][bj][m][n] = __builtin_amdgcn_mfma_f32_16x16x32_bf16(Bt[n][k], At[m][k], acc[ai][bj][m][n], 0, 0, 0); __builtin_amdgcn_s_setprio(0); } while (0)
; #define PG8_WAIT_V(n) asm volatile("s_waitcnt vmcnt(" #n ")" ::: "memory")
; #define PG8_WAIT_L(n) asm volatile("s_waitcnt lgkmcnt(" #n ")" ::: "memory")
; #define PG8_BAR __builtin_amdgcn_s_barrier()
; #define PG8_SCHED __builtin_amdgcn_sched_barrier(0)
; template <class Epi, bool ALIGN_EPI>
; __device__ __forceinline__ void gemm_phase(LAS unsigned char* lds, const Gemm g, const StaticOrder& S, const Epi& E, const int tid) {
;     ...
;             PG8_LDB(B0, 0, 0); PG8_LDB(B1, 0, 1); PG8_SCHED; PG8_LDA(At, 0, 0); PG8_STAGE(PG8_SA(1, 1), a1 + hA, voffA);
;             PG8_WAIT_V(8); PG8_WAIT_L(0); PG8_BAR; PG8_MMA(0, 0, At, B0); PG8_MMA(0, 1, At, B1); PG8_BAR; PG8_SCHED;
;             PG8_LDA(At, 0, 1); PG8_STAGE(PG8_SB(0, 0), b2, voffB); PG8_STAGE(PG8_SB(0, 1), b2 + hB, voffB); PG8_STAGE(PG8_SA(0, 0), a2, voffA);
.Lgu_last:
	s_add_i32 s11, s10, 2
	s_cmp_eq_u32 s58, s10
	v_lshl_add_u64 v[146:147], v[142:143], 0, s[92:93]
	s_cselect_b64 vcc, -1, 0
	v_add_u32_e32 v150, s33, v151
	s_add_i32 s10, 0, 0x14000
	v_cndmask_b32_e32 v167, v147, v139, vcc
	v_cndmask_b32_e32 v166, v146, v138, vcc
	ds_read_b128 v[146:149], v150
	ds_read_b128 v[154:157], v150 offset:1024
	ds_read_b128 v[158:161], v150 offset:2048
	ds_read_b128 v[162:165], v150 offset:3072
	v_add_u32_e32 v150, s10, v151
	ds_read_b128 v[176:179], v150
	ds_read_b128 v[180:183], v150 offset:1024
	ds_read_b128 v[184:187], v150 offset:2048
	ds_read_b128 v[188:191], v150 offset:3072
	v_cndmask_b32_e32 v221, v145, v141, vcc
	v_cndmask_b32_e32 v220, v144, v140, vcc
	v_lshl_add_u64 v[226:227], v[142:143], 0, v[134:135]
	s_add_i32 m0, s51, 0xc000
	ds_read_b128 v[192:195], v153
	ds_read_b128 v[196:199], v153 offset:1024
	ds_read_b128 v[200:203], v153 offset:2048
	ds_read_b128 v[204:207], v153 offset:3072
	ds_read_b128 v[208:211], v153 offset:4096
	ds_read_b128 v[212:215], v153 offset:5120
	ds_read_b128 v[216:219], v153 offset:6144
	ds_read_b128 v[240:243], v153 offset:7168
	global_load_lds_dwordx4 v[226:227], off
	v_lshl_add_u64 v[226:227], v[142:143], 0, v[136:137]
	s_add_i32 m0, s51, 0xe000
	s_nop 0
	global_load_lds_dwordx4 v[226:227], off
	s_waitcnt vmcnt(8)
	s_waitcnt lgkmcnt(0)
	s_barrier
	s_setprio 1
	s_waitcnt lgkmcnt(0)
	v_mfma_f32_16x16x32_bf16 v[120:123], v[146:149], v[192:195], v[120:123]
	v_mfma_f32_16x16x32_bf16 v[112:115], v[158:161], v[192:195], v[112:115]
	v_mfma_f32_16x16x32_bf16 v[104:107], v[146:149], v[200:203], v[104:107]
	v_mfma_f32_16x16x32_bf16 v[96:99], v[158:161], v[200:203], v[96:99]
	v_mfma_f32_16x16x32_bf16 v[88:91], v[146:149], v[208:211], v[88:91]
	v_mfma_f32_16x16x32_bf16 v[80:83], v[158:161], v[208:211], v[80:83]
	v_mfma_f32_16x16x32_bf16 v[72:75], v[146:149], v[216:219], v[72:75]
	v_mfma_f32_16x16x32_bf16 v[64:67], v[158:161], v[216:219], v[64:67]
	v_mfma_f32_16x16x32_bf16 v[120:123], v[154:157], v[196:199], v[120:123]
	v_mfma_f32_16x16x32_bf16 v[112:115], v[162:165], v[196:199], v[112:115]
	v_mfma_f32_16x16x32_bf16 v[104:107], v[154:157], v[204:207], v[104:107]
	v_mfma_f32_16x16x32_bf16 v[96:99], v[162:165], v[204:207], v[96:99]
	v_mfma_f32_16x16x32_bf16 v[88:91], v[154:157], v[212:215], v[88:91]
	v_mfma_f32_16x16x32_bf16 v[80:83], v[162:165], v[212:215], v[80:83]
	v_mfma_f32_16x16x32_bf16 v[72:75], v[154:157], v[240:243], v[72:75]
	v_mfma_f32_16x16x32_bf16 v[64:67], v[162:165], v[240:243], v[64:67]
	s_setprio 0
	s_setprio 1
	v_mfma_f32_16x16x32_bf16 v[124:127], v[176:179], v[192:195], v[124:127]
	v_mfma_f32_16x16x32_bf16 v[116:119], v[184:187], v[192:195], v[116:119]
	v_mfma_f32_16x16x32_bf16 v[108:111], v[176:179], v[200:203], v[108:111]
	v_mfma_f32_16x16x32_bf16 v[100:103], v[184:187], v[200:203], v[100:103]
	v_mfma_f32_16x16x32_bf16 v[92:95], v[176:179], v[208:211], v[92:95]
	v_mfma_f32_16x16x32_bf16 v[84:87], v[184:187], v[208:211], v[84:87]
	v_mfma_f32_16x16x32_bf16 v[76:79], v[176:179], v[216:219], v[76:79]
	v_mfma_f32_16x16x32_bf16 v[68:71], v[184:187], v[216:219], v[68:71]
	v_mfma_f32_16x16x32_bf16 v[124:127], v[180:183], v[196:199], v[124:127]
	v_mfma_f32_16x16x32_bf16 v[116:119], v[188:191], v[196:199], v[116:119]
	v_mfma_f32_16x16x32_bf16 v[108:111], v[180:183], v[204:207], v[108:111]
	v_mfma_f32_16x16x32_bf16 v[100:103], v[188:191], v[204:207], v[100:103]
	v_mfma_f32_16x16x32_bf16 v[92:95], v[180:183], v[212:215], v[92:95]
	v_mfma_f32_16x16x32_bf16 v[84:87], v[188:191], v[212:215], v[84:87]
	v_mfma_f32_16x16x32_bf16 v[76:79], v[180:183], v[240:243], v[76:79]
	v_mfma_f32_16x16x32_bf16 v[68:71], v[188:191], v[240:243], v[68:71]
	s_setprio 0
	s_barrier
	s_add_i32 s65, s33, s45
	v_lshl_add_u64 v[226:227], v[220:221], 0, v[168:169]
	s_mov_b32 m0, s65
	ds_read_b128 v[192:195], v153 offset:16384
	ds_read_b128 v[196:199], v153 offset:17408
	ds_read_b128 v[200:203], v153 offset:18432
	ds_read_b128 v[204:207], v153 offset:19456
	ds_read_b128 v[208:211], v153 offset:20480
	ds_read_b128 v[212:215], v153 offset:21504
	ds_read_b128 v[216:219], v153 offset:22528
	ds_read_b128 v[240:243], v153 offset:23552
	global_load_lds_dwordx4 v[226:227], off
	v_lshl_add_u64 v[244:245], v[220:221], 0, v[128:129]
	s_add_i32 m0, s65, 0x2000
	v_lshl_add_u64 v[220:221], v[220:221], 0, s[12:13]
	s_add_i32 s10, s10, s45
	global_load_lds_dwordx4 v[244:245], off
	v_lshl_add_u64 v[246:247], v[220:221], 0, v[168:169]
	s_mov_b32 m0, s10
	v_lshl_add_u64 v[220:221], v[220:221], 0, v[128:129]
	global_load_lds_dwordx4 v[246:247], off
	s_add_i32 m0, s10, 0x2000
	v_lshl_add_u64 v[248:249], v[166:167], 0, v[132:133]
	global_load_lds_dwordx4 v[220:221], off
	s_mov_b32 m0, s51
	v_lshl_add_u64 v[250:251], v[166:167], 0, v[130:131]
	global_load_lds_dwordx4 v[248:249], off
	s_mov_b32 m0, s52
	s_nop 0
	global_load_lds_dwordx4 v[250:251], off
	s_waitcnt vmcnt(8)
	s_waitcnt lgkmcnt(0)
	s_barrier
; #define PG8_STAGE(bufoff, gbase, voff) do { _Pragma("unroll") for (int _i = 0; _i < 2; ++_i) \
;         __builtin_amdgcn_global_load_lds((const unsigned*)((const char*)(gbase) + (voff)[_i]), (LAS unsigned*)(lds + (bufoff) + ldsw + _i * 8192), 16, 0, 0); } while (0)
; #define PG8_LDA(dst, b, h) do { _Pragma("unroll") for (int m = 0; m < 4; ++m) _Pragma("unroll") for (int k = 0; k < 2; ++k) dst[m][k] = *(const LAS bf16x8*)(lds + PG8_SA(b, h) + aoff + m * 2048 + k * 1024); } while (0)
; #define PG8_LDB(dst, b, h) do { _Pragma("unroll") for (int n = 0; n < 2; ++n) _Pragma("unroll") for (int k = 0; k < 2; ++k) dst[n][k] = *(const LAS bf16x8*)(lds + PG8_SB(b, h) + boff + n * 2048 + k * 1024); } while (0)
; #define PG8_MMA(ai, bj, At, Bt) do { __builtin_amdgcn_s_setprio(1); _Pragma("unroll") for (int k = 0; k < 2; ++k) _Pragma("unroll") for (int m = 0; m < 4; ++m) _Pragma("unroll") for (int n = 0; n < 2; ++n) \
;         acc[ai][bj][m][n] = __builtin_amdgcn_mfma_f32_16x16x32_bf16(Bt[n][k], At[m][k], acc[ai][bj][m][n], 0, 0, 0); __builtin_amdgcn_s_setprio(0); } while (0)
; #define PG8_WAIT_V(n) asm volatile("s_waitcnt vmcnt(" #n ")" ::: "memory")
; #define PG8_WAIT_L(n) asm volatile("s_waitcnt lgkmcnt(" #n ")" ::: "memory")
; #define PG8_BAR __builtin_amdgcn_s_barrier()
; #define PG8_SCHED __builtin_amdgcn_sched_barrier(0)
; template <class Epi, bool ALIGN_EPI>
; __device__ __forceinline__ void gemm_phase(LAS unsigned char* lds, const Gemm g, const StaticOrder& S, const Epi& E, const int tid) {
;     ...
;             PG8_WAIT_V(8); PG8_WAIT_L(0); PG8_BAR; PG8_MMA(1, 0, At, B0); PG8_MMA(1, 1, At, B1); PG8_BAR; PG8_SCHED;
;             PG8_LDB(B0, 1, 0); PG8_LDB(B1, 1, 1); PG8_SCHED; PG8_LDA(At, 1, 0); PG8_STAGE(PG8_SA(0, 1), a2 + hA, voffA);
;             PG8_WAIT_V(8); PG8_WAIT_L(0); PG8_BAR; PG8_MMA(0, 0, At, B0); PG8_MMA(0, 1, At, B1); PG8_BAR; PG8_SCHED;
	s_setprio 1
	s_waitcnt lgkmcnt(0)
	v_mfma_f32_16x16x32_bf16 v[56:59], v[146:149], v[192:195], v[56:59]
	v_mfma_f32_16x16x32_bf16 v[48:51], v[158:161], v[192:195], v[48:51]
	v_mfma_f32_16x16x32_bf16 v[40:43], v[146:149], v[200:203], v[40:43]
	v_mfma_f32_16x16x32_bf16 v[32:35], v[158:161], v[200:203], v[32:35]
	v_mfma_f32_16x16x32_bf16 v[24:27], v[146:149], v[208:211], v[24:27]
	v_mfma_f32_16x16x32_bf16 v[16:19], v[158:161], v[208:211], v[16:19]
	v_mfma_f32_16x16x32_bf16 v[8:11], v[146:149], v[216:219], v[8:11]
	v_mfma_f32_16x16x32_bf16 v[4:7], v[158:161], v[216:219], v[4:7]
	v_mfma_f32_16x16x32_bf16 v[56:59], v[154:157], v[196:199], v[56:59]
	v_mfma_f32_16x16x32_bf16 v[48:51], v[162:165], v[196:199], v[48:51]
	v_mfma_f32_16x16x32_bf16 v[40:43], v[154:157], v[204:207], v[40:43]
	v_mfma_f32_16x16x32_bf16 v[32:35], v[162:165], v[204:207], v[32:35]
	v_mfma_f32_16x16x32_bf16 v[24:27], v[154:157], v[212:215], v[24:27]
	v_mfma_f32_16x16x32_bf16 v[16:19], v[162:165], v[212:215], v[16:19]
	v_mfma_f32_16x16x32_bf16 v[8:11], v[154:157], v[240:243], v[8:11]
	v_mfma_f32_16x16x32_bf16 v[4:7], v[162:165], v[240:243], v[4:7]
	s_setprio 0
	s_setprio 1
	v_mfma_f32_16x16x32_bf16 v[60:63], v[176:179], v[192:195], v[60:63]
	v_mfma_f32_16x16x32_bf16 v[52:55], v[184:187], v[192:195], v[52:55]
	v_mfma_f32_16x16x32_bf16 v[44:47], v[176:179], v[200:203], v[44:47]
	v_mfma_f32_16x16x32_bf16 v[36:39], v[184:187], v[200:203], v[36:39]
	v_mfma_f32_16x16x32_bf16 v[28:31], v[176:179], v[208:211], v[28:31]
	v_mfma_f32_16x16x32_bf16 v[20:23], v[184:187], v[208:211], v[20:23]
	v_mfma_f32_16x16x32_bf16 v[12:15], v[176:179], v[216:219], v[12:15]
	v_mfma_f32_16x16x32_bf16 v[0:3], v[184:187], v[216:219], v[0:3]
	v_mfma_f32_16x16x32_bf16 v[60:63], v[180:183], v[196:199], v[60:63]
	v_mfma_f32_16x16x32_bf16 v[52:55], v[188:191], v[196:199], v[52:55]
	v_mfma_f32_16x16x32_bf16 v[44:47], v[180:183], v[204:207], v[44:47]
	v_mfma_f32_16x16x32_bf16 v[36:39], v[188:191], v[204:207], v[36:39]
	v_mfma_f32_16x16x32_bf16 v[28:31], v[180:183], v[212:215], v[28:31]
	v_mfma_f32_16x16x32_bf16 v[20:23], v[188:191], v[212:215], v[20:23]
	v_mfma_f32_16x16x32_bf16 v[12:15], v[180:183], v[240:243], v[12:15]
	v_mfma_f32_16x16x32_bf16 v[0:3], v[188:191], v[240:243], v[0:3]
	s_setprio 0
	s_barrier
	s_add_i32 s10, 0, 0x18000
	v_add_u32_e32 v150, s10, v151
	s_add_i32 s65, 0, 0x1c000
	ds_read_b128 v[146:149], v150
	ds_read_b128 v[154:157], v150 offset:1024
	ds_read_b128 v[158:161], v150 offset:2048
	ds_read_b128 v[162:165], v150 offset:3072
	v_add_u32_e32 v150, s65, v151
	ds_read_b128 v[176:179], v150
	ds_read_b128 v[180:183], v150 offset:1024
	ds_read_b128 v[184:187], v150 offset:2048
	ds_read_b128 v[188:191], v150 offset:3072
	v_lshl_add_u64 v[166:167], v[166:167], 0, s[94:95]
	s_mov_b32 m0, s53
	v_lshl_add_u64 v[252:253], v[166:167], 0, v[132:133]
	ds_read_b128 v[192:195], v153 offset:32768
	ds_read_b128 v[196:199], v153 offset:33792
	ds_read_b128 v[200:203], v153 offset:34816
	ds_read_b128 v[204:207], v153 offset:35840
	ds_read_b128 v[208:211], v153 offset:36864
	ds_read_b128 v[212:215], v153 offset:37888
	ds_read_b128 v[216:219], v153 offset:38912
	ds_read_b128 v[240:243], v153 offset:39936
	global_load_lds_dwordx4 v[252:253], off
	v_lshl_add_u64 v[166:167], v[166:167], 0, v[130:131]
	s_mov_b32 m0, s54
	s_nop 0
	global_load_lds_dwordx4 v[166:167], off
	s_waitcnt vmcnt(8)
	s_waitcnt lgkmcnt(0)
	s_barrier
	s_setprio 1
	s_waitcnt lgkmcnt(0)
	v_mfma_f32_16x16x32_bf16 v[120:123], v[146:149], v[192:195], v[120:123]
	v_mfma_f32_16x16x32_bf16 v[112:115], v[158:161], v[192:195], v[112:115]
	v_mfma_f32_16x16x32_bf16 v[104:107], v[146:149], v[200:203], v[104:107]
	v_mfma_f32_16x16x32_bf16 v[96:99], v[158:161], v[200:203], v[96:99]
	v_mfma_f32_16x16x32_bf16 v[88:91], v[146:149], v[208:211], v[88:91]
	v_mfma_f32_16x16x32_bf16 v[80:83], v[158:161], v[208:211], v[80:83]
	v_mfma_f32_16x16x32_bf16 v[72:75], v[146:149], v[216:219], v[72:75]
	v_mfma_f32_16x16x32_bf16 v[64:67], v[158:161], v[216:219], v[64:67]
	v_mfma_f32_16x16x32_bf16 v[120:123], v[154:157], v[196:199], v[120:123]
	v_mfma_f32_16x16x32_bf16 v[112:115], v[162:165], v[196:199], v[112:115]
	v_mfma_f32_16x16x32_bf16 v[104:107], v[154:157], v[204:207], v[104:107]
	v_mfma_f32_16x16x32_bf16 v[96:99], v[162:165], v[204:207], v[96:99]
	v_mfma_f32_16x16x32_bf16 v[88:91], v[154:157], v[212:215], v[88:91]
	v_mfma_f32_16x16x32_bf16 v[80:83], v[162:165], v[212:215], v[80:83]
	v_mfma_f32_16x16x32_bf16 v[72:75], v[154:157], v[240:243], v[72:75]
	v_mfma_f32_16x16x32_bf16 v[64:67], v[162:165], v[240:243], v[64:67]
	s_setprio 0
	s_setprio 1
	v_mfma_f32_16x16x32_bf16 v[124:127], v[176:179], v[192:195], v[124:127]
	v_mfma_f32_16x16x32_bf16 v[116:119], v[184:187], v[192:195], v[116:119]
	v_mfma_f32_16x16x32_bf16 v[108:111], v[176:179], v[200:203], v[108:111]
	v_mfma_f32_16x16x32_bf16 v[100:103], v[184:187], v[200:203], v[100:103]
	v_mfma_f32_16x16x32_bf16 v[92:95], v[176:179], v[208:211], v[92:95]
	v_mfma_f32_16x16x32_bf16 v[84:87], v[184:187], v[208:211], v[84:87]
	v_mfma_f32_16x16x32_bf16 v[76:79], v[176:179], v[216:219], v[76:79]
	v_mfma_f32_16x16x32_bf16 v[68:71], v[184:187], v[216:219], v[68:71]
	v_mfma_f32_16x16x32_bf16 v[124:127], v[180:183], v[196:199], v[124:127]
	v_mfma_f32_16x16x32_bf16 v[116:119], v[188:191], v[196:199], v[116:119]
	v_mfma_f32_16x16x32_bf16 v[108:111], v[180:183], v[204:207], v[108:111]
	v_mfma_f32_16x16x32_bf16 v[100:103], v[188:191], v[204:207], v[100:103]
	v_mfma_f32_16x16x32_bf16 v[92:95], v[180:183], v[212:215], v[92:95]
	v_mfma_f32_16x16x32_bf16 v[84:87], v[188:191], v[212:215], v[84:87]
	v_mfma_f32_16x16x32_bf16 v[76:79], v[180:183], v[240:243], v[76:79]
	v_mfma_f32_16x16x32_bf16 v[68:71], v[188:191], v[240:243], v[68:71]
	s_setprio 0
	s_barrier
; __device__ __forceinline__ unsigned cvt_pk_bf16(float lo, float hi) { unsigned r; asm volatile("v_cvt_pk_bf16_f32 %0, %1, %2" : "=v"(r) : "v"(lo), "v"(hi)); return r; }
; __device__ __forceinline__ float siluf_(float x) { return x * sigmoidf_(x); }
; #define PG8_STAGE(bufoff, gbase, voff) do { _Pragma("unroll") for (int _i = 0; _i < 2; ++_i) \
;         __builtin_amdgcn_global_load_lds((const unsigned*)((const char*)(gbase) + (voff)[_i]), (LAS unsigned*)(lds + (bufoff) + ldsw + _i * 8192), 16, 0, 0); } while (0)
; #define PG8_LDA(dst, b, h) do { _Pragma("unroll") for (int m = 0; m < 4; ++m) _Pragma("unroll") for (int k = 0; k < 2; ++k) dst[m][k] = *(const LAS bf16x8*)(lds + PG8_SA(b, h) + aoff + m * 2048 + k * 1024); } while (0)
; #define PG8_WAIT_V(n) asm volatile("s_waitcnt vmcnt(" #n ")" ::: "memory")
; #define PG8_WAIT_L(n) asm volatile("s_waitcnt lgkmcnt(" #n ")" ::: "memory")
; #define PG8_BAR __builtin_amdgcn_s_barrier()
; #define PG8_SCHED __builtin_amdgcn_sched_barrier(0)
;     __device__ __forceinline__ void operator()(const f32x4 (&acc)[2][2][4][2], const Unit& u, int wr, int wc, int fr, int fq) const {
;         const int row0 = u.pm * BM + wr * 64 + fr, col0 = u.pn * HALF + wc * 32 + 8 * fq;
;         float rsv[2][4]; load_rstd(rsv, ssq, row0);
; #pragma unroll
;         for (int ai = 0; ai < 2; ++ai)
; #pragma unroll
;             for (int m = 0; m < 4; ++m) { const int row = row0 + ai * HALF + m * 16; bf16_t* rowp = O + (size_t)row * ldc + col0; const float rs = rsv[ai][m];
;                 f32x4 v0, v1;
; #pragma unroll
;                 for (int j = 0; j < 4; ++j) { v0[j] = siluf_(acc[ai][0][m][0][j] * rs) * (acc[ai][1][m][0][j] * rs); v1[j] = siluf_(acc[ai][0][m][1][j] * rs) * (acc[ai][1][m][1][j] * rs); }
;                 u32x4 w; w.x = cvt_pk_bf16(v0[0], v0[1]); w.y = cvt_pk_bf16(v0[2], v0[3]); w.z = cvt_pk_bf16(v1[0], v1[1]); w.w = cvt_pk_bf16(v1[2], v1[3]);
;                 *(u32x4*)rowp = w; }
; template <class Epi, bool ALIGN_EPI>
; __device__ __forceinline__ void gemm_phase(LAS unsigned char* lds, const Gemm g, const StaticOrder& S, const Epi& E, const int tid) {
;     ...
;             PG8_LDA(At, 1, 1); PG8_STAGE(PG8_SB(1, 0), b3, voffB); PG8_STAGE(PG8_SB(1, 1), b3 + hB, voffB); PG8_STAGE(PG8_SA(1, 0), a3, voffA);
;             PG8_WAIT_V(8); PG8_WAIT_L(0); PG8_BAR; PG8_MMA(1, 0, At, B0); PG8_MMA(1, 1, At, B1); PG8_BAR; PG8_SCHED;
	s_add_i32 s10, s10, s45
	v_lshl_add_u64 v[166:167], v[226:227], 0, s[92:93]
	s_mov_b32 m0, s10
	ds_read_b128 v[192:195], v153 offset:49152
	ds_read_b128 v[196:199], v153 offset:50176
	ds_read_b128 v[200:203], v153 offset:51200
	ds_read_b128 v[204:207], v153 offset:52224
	ds_read_b128 v[208:211], v153 offset:53248
	ds_read_b128 v[212:215], v153 offset:54272
	ds_read_b128 v[216:219], v153 offset:55296
	ds_read_b128 v[240:243], v153 offset:56320
	global_load_lds_dwordx4 v[166:167], off
	v_lshl_add_u64 v[166:167], v[244:245], 0, s[92:93]
	s_add_i32 m0, s10, 0x2000
	s_add_i32 s10, s65, s45
	global_load_lds_dwordx4 v[166:167], off
	v_lshl_add_u64 v[166:167], v[246:247], 0, s[92:93]
	s_mov_b32 m0, s10
	s_nop 0
	global_load_lds_dwordx4 v[166:167], off
	v_lshl_add_u64 v[166:167], v[220:221], 0, s[92:93]
	s_add_i32 m0, s10, 0x2000
	s_nop 0
	global_load_lds_dwordx4 v[166:167], off
	v_lshl_add_u64 v[166:167], v[248:249], 0, s[92:93]
	s_mov_b32 m0, s56
	s_nop 0
	global_load_lds_dwordx4 v[166:167], off
	v_lshl_add_u64 v[166:167], v[250:251], 0, s[92:93]
	s_mov_b32 m0, s57
	s_nop 0
	global_load_lds_dwordx4 v[166:167], off
	s_waitcnt vmcnt(8)
	s_waitcnt lgkmcnt(0)
	s_barrier
	s_waitcnt lgkmcnt(0)
	v_mfma_f32_16x16x32_bf16 v[56:59], v[146:149], v[192:195], v[56:59]
	v_lshrrev_b32_e32 v171, 8, v170
	v_and_b32_e32 v234, 15, v170
	v_lshl_add_u32 v171, v171, 6, v234
	s_lshl_b32 s98, s64, 8
	v_add_u32_e32 v171, s98, v171
	v_mul_lo_u32 v171, v171, s28
	v_bfe_u32 v234, v170, 6, 2
	v_bfe_u32 v224, v170, 4, 2
	v_lshlrev_b32_e32 v234, 5, v234
	v_lshl_or_b32 v234, v224, 3, v234
	v_mfma_f32_16x16x32_bf16 v[48:51], v[158:161], v[192:195], v[48:51]
	s_lshl_b32 s98, s63, 7
	v_add_u32_e32 v234, s98, v234
	v_add_lshl_u32 v232, v171, v234, 1
	v_mov_b32_e32 v233, 0
	v_lshl_add_u64 v[232:233], v[232:233], 0, s[30:31]
	s_lshl_b32 s98, s28, 5
	s_mov_b32 s99, 0
	s_mov_b32 s100, 0xbfb8aa3b
	s_mov_b32 s101, 0xbfb8aa3b
	v_mul_f32_e32 v120, v172, v120
	v_mfma_f32_16x16x32_bf16 v[40:43], v[146:149], v[200:203], v[40:43]
	v_mul_f32_e32 v121, v172, v121
	v_mul_f32_e32 v122, v172, v122
	v_mul_f32_e32 v123, v172, v123
	v_mul_f32_e32 v124, v172, v124
	v_mul_f32_e32 v125, v172, v125
	v_mul_f32_e32 v126, v172, v126
	v_mul_f32_e32 v127, v172, v127
	v_mul_f32_e32 v224, s100, v120
	v_mul_f32_e32 v225, s101, v121
	v_mul_f32_e32 v228, s100, v122
	v_mfma_f32_16x16x32_bf16 v[32:35], v[158:161], v[200:203], v[32:35]
	v_mul_f32_e32 v229, s101, v123
	v_exp_f32_e32 v224, v224
	v_exp_f32_e32 v225, v225
	v_exp_f32_e32 v228, v228
	v_exp_f32_e32 v229, v229
	v_add_f32_e32 v224, 1.0, v224
	v_add_f32_e32 v225, 1.0, v225
	v_add_f32_e32 v228, 1.0, v228
	v_add_f32_e32 v229, 1.0, v229
	v_rcp_f32_e32 v224, v224
	v_mfma_f32_16x16x32_bf16 v[24:27], v[146:149], v[208:211], v[24:27]
	v_rcp_f32_e32 v225, v225
	v_rcp_f32_e32 v228, v228
	v_rcp_f32_e32 v229, v229
	v_nop
	v_mul_f32_e32 v120, v224, v120
	v_mul_f32_e32 v121, v225, v121
	v_mul_f32_e32 v122, v228, v122
	v_mul_f32_e32 v123, v229, v123
	v_mul_f32_e32 v120, v124, v120
	v_mul_f32_e32 v121, v125, v121
	v_mfma_f32_16x16x32_bf16 v[16:19], v[158:161], v[208:211], v[16:19]
	v_mul_f32_e32 v122, v126, v122
	v_mul_f32_e32 v123, v127, v123
	v_mul_f32_e32 v112, v172, v112
	v_mul_f32_e32 v113, v172, v113
	v_mul_f32_e32 v114, v172, v114
	v_mul_f32_e32 v115, v172, v115
	v_mul_f32_e32 v116, v172, v116
	v_mul_f32_e32 v117, v172, v117
	v_mul_f32_e32 v118, v172, v118
	v_mul_f32_e32 v119, v172, v119
	v_mfma_f32_16x16x32_bf16 v[8:11], v[146:149], v[216:219], v[8:11]
	v_mul_f32_e32 v224, s100, v112
	v_mul_f32_e32 v225, s101, v113
	v_mul_f32_e32 v228, s100, v114
	v_mul_f32_e32 v229, s101, v115
	v_exp_f32_e32 v224, v224
	v_exp_f32_e32 v225, v225
	v_exp_f32_e32 v228, v228
	v_exp_f32_e32 v229, v229
	v_add_f32_e32 v224, 1.0, v224
	v_add_f32_e32 v225, 1.0, v225
	v_mfma_f32_16x16x32_bf16 v[4:7], v[158:161], v[216:219], v[4:7]
	v_add_f32_e32 v228, 1.0, v228
	v_add_f32_e32 v229, 1.0, v229
	v_rcp_f32_e32 v224, v224
	v_rcp_f32_e32 v225, v225
	v_rcp_f32_e32 v228, v228
	v_rcp_f32_e32 v229, v229
	v_nop
	v_mul_f32_e32 v112, v224, v112
	v_mul_f32_e32 v113, v225, v113
	v_mul_f32_e32 v114, v228, v114
	v_mfma_f32_16x16x32_bf16 v[56:59], v[154:157], v[196:199], v[56:59]
	v_mul_f32_e32 v115, v229, v115
	v_mul_f32_e32 v112, v116, v112
	v_mul_f32_e32 v113, v117, v113
	v_mul_f32_e32 v114, v118, v114
	v_mul_f32_e32 v115, v119, v115
	v_cvt_pk_bf16_f32 v120, v120, v121
	v_cvt_pk_bf16_f32 v121, v122, v123
	v_cvt_pk_bf16_f32 v122, v112, v113
	v_cvt_pk_bf16_f32 v123, v114, v115
	global_store_dwordx4 v[232:233], v[120:123], off
	v_mfma_f32_16x16x32_bf16 v[48:51], v[162:165], v[196:199], v[48:51]
	v_lshl_add_u64 v[232:233], v[232:233], 0, s[98:99]
	v_mul_f32_e32 v104, v173, v104
	v_mul_f32_e32 v105, v173, v105
	v_mul_f32_e32 v106, v173, v106
	v_mul_f32_e32 v107, v173, v107
	v_mul_f32_e32 v108, v173, v108
	v_mul_f32_e32 v109, v173, v109
	v_mul_f32_e32 v110, v173, v110
	v_mul_f32_e32 v111, v173, v111
	v_mul_f32_e32 v224, s100, v104
	v_mfma_f32_16x16x32_bf16 v[40:43], v[154:157], v[204:207], v[40:43]
	v_mul_f32_e32 v225, s101, v105
	v_mul_f32_e32 v228, s100, v106
	v_mul_f32_e32 v229, s101, v107
	v_exp_f32_e32 v224, v224
	v_exp_f32_e32 v225, v225
	v_exp_f32_e32 v228, v228
	v_exp_f32_e32 v229, v229
	v_add_f32_e32 v224, 1.0, v224
	v_add_f32_e32 v225, 1.0, v225
	v_add_f32_e32 v228, 1.0, v228
	v_mfma_f32_16x16x32_bf16 v[32:35], v[162:165], v[204:207], v[32:35]
	v_add_f32_e32 v229, 1.0, v229
	v_rcp_f32_e32 v224, v224
	v_rcp_f32_e32 v225, v225
	v_rcp_f32_e32 v228, v228
	v_rcp_f32_e32 v229, v229
	v_nop
	v_mul_f32_e32 v104, v224, v104
	v_mul_f32_e32 v105, v225, v105
	v_mul_f32_e32 v106, v228, v106
	v_mul_f32_e32 v107, v229, v107
; __device__ __forceinline__ unsigned cvt_pk_bf16(float lo, float hi) { unsigned r; asm volatile("v_cvt_pk_bf16_f32 %0, %1, %2" : "=v"(r) : "v"(lo), "v"(hi)); return r; }
; __device__ __forceinline__ float siluf_(float x) { return x * sigmoidf_(x); }
; #define PG8_STAGE(bufoff, gbase, voff) do { _Pragma("unroll") for (int _i = 0; _i < 2; ++_i) \
;         __builtin_amdgcn_global_load_lds((const unsigned*)((const char*)(gbase) + (voff)[_i]), (LAS unsigned*)(lds + (bufoff) + ldsw + _i * 8192), 16, 0, 0); } while (0)
; #define PG8_LDA(dst, b, h) do { _Pragma("unroll") for (int m = 0; m < 4; ++m) _Pragma("unroll") for (int k = 0; k < 2; ++k) dst[m][k] = *(const LAS bf16x8*)(lds + PG8_SA(b, h) + aoff + m * 2048 + k * 1024); } while (0)
; #define PG8_MMA(ai, bj, At, Bt) do { __builtin_amdgcn_s_setprio(1); _Pragma("unroll") for (int k = 0; k < 2; ++k) _Pragma("unroll") for (int m = 0; m < 4; ++m) _Pragma("unroll") for (int n = 0; n < 2; ++n) \
;         acc[ai][bj][m][n] = __builtin_amdgcn_mfma_f32_16x16x32_bf16(Bt[n][k], At[m][k], acc[ai][bj][m][n], 0, 0, 0); __builtin_amdgcn_s_setprio(0); } while (0)
; #define PG8_WAIT_V(n) asm volatile("s_waitcnt vmcnt(" #n ")" ::: "memory")
;     __device__ __forceinline__ void operator()(const f32x4 (&acc)[2][2][4][2], const Unit& u, int wr, int wc, int fr, int fq) const {
;     ...
;             for (int m = 0; m < 4; ++m) { const int row = row0 + ai * HALF + m * 16; bf16_t* rowp = O + (size_t)row * ldc + col0; const float rs = rsv[ai][m];
;                 f32x4 v0, v1;
; #pragma unroll
;                 for (int j = 0; j < 4; ++j) { v0[j] = siluf_(acc[ai][0][m][0][j] * rs) * (acc[ai][1][m][0][j] * rs); v1[j] = siluf_(acc[ai][0][m][1][j] * rs) * (acc[ai][1][m][1][j] * rs); }
;                 u32x4 w; w.x = cvt_pk_bf16(v0[0], v0[1]); w.y = cvt_pk_bf16(v0[2], v0[3]); w.z = cvt_pk_bf16(v1[0], v1[1]); w.w = cvt_pk_bf16(v1[2], v1[3]);
;                 *(u32x4*)rowp = w; }
; template <class Epi, bool ALIGN_EPI>
; __device__ __forceinline__ void gemm_phase(LAS unsigned char* lds, const Gemm g, const StaticOrder& S, const Epi& E, const int tid) {
;     ...
;             PG8_LDA(At, 1, 1); PG8_STAGE(PG8_SB(1, 0), b3, voffB); PG8_STAGE(PG8_SB(1, 1), b3 + hB, voffB); PG8_STAGE(PG8_SA(1, 0), a3, voffA);
;             PG8_WAIT_V(8); PG8_WAIT_L(0); PG8_BAR; PG8_MMA(1, 0, At, B0); PG8_MMA(1, 1, At, B1); PG8_BAR; PG8_SCHED;
	v_mfma_f32_16x16x32_bf16 v[24:27], v[154:157], v[212:215], v[24:27]
	v_mul_f32_e32 v104, v108, v104
	v_mul_f32_e32 v105, v109, v105
	v_mul_f32_e32 v106, v110, v106
	v_mul_f32_e32 v107, v111, v107
	v_mul_f32_e32 v96, v173, v96
	v_mul_f32_e32 v97, v173, v97
	v_mul_f32_e32 v98, v173, v98
	v_mul_f32_e32 v99, v173, v99
	v_mul_f32_e32 v100, v173, v100
	v_mul_f32_e32 v101, v173, v101
	v_mfma_f32_16x16x32_bf16 v[16:19], v[162:165], v[212:215], v[16:19]
	v_mul_f32_e32 v102, v173, v102
	v_mul_f32_e32 v103, v173, v103
	v_mul_f32_e32 v224, s100, v96
	v_mul_f32_e32 v225, s101, v97
	v_mul_f32_e32 v228, s100, v98
	v_mul_f32_e32 v229, s101, v99
	v_exp_f32_e32 v224, v224
	v_exp_f32_e32 v225, v225
	v_exp_f32_e32 v228, v228
	v_exp_f32_e32 v229, v229
	v_mfma_f32_16x16x32_bf16 v[8:11], v[154:157], v[240:243], v[8:11]
	v_add_f32_e32 v224, 1.0, v224
	v_add_f32_e32 v225, 1.0, v225
	v_add_f32_e32 v228, 1.0, v228
	v_add_f32_e32 v229, 1.0, v229
	v_rcp_f32_e32 v224, v224
	v_rcp_f32_e32 v225, v225
	v_rcp_f32_e32 v228, v228
	v_rcp_f32_e32 v229, v229
	v_nop
	v_mul_f32_e32 v96, v224, v96
	v_mfma_f32_16x16x32_bf16 v[4:7], v[162:165], v[240:243], v[4:7]
	v_mul_f32_e32 v97, v225, v97
	v_mul_f32_e32 v98, v228, v98
	v_mul_f32_e32 v99, v229, v99
	v_mul_f32_e32 v96, v100, v96
	v_mul_f32_e32 v97, v101, v97
	v_mul_f32_e32 v98, v102, v98
	v_mul_f32_e32 v99, v103, v99
	v_cvt_pk_bf16_f32 v104, v104, v105
	v_cvt_pk_bf16_f32 v105, v106, v107
	v_cvt_pk_bf16_f32 v106, v96, v97
	s_setprio 0
	v_mfma_f32_16x16x32_bf16 v[60:63], v[176:179], v[192:195], v[60:63]
	v_cvt_pk_bf16_f32 v107, v98, v99
	global_store_dwordx4 v[232:233], v[104:107], off
	v_lshl_add_u64 v[232:233], v[232:233], 0, s[98:99]
	v_mul_f32_e32 v88, v236, v88
	v_mul_f32_e32 v89, v236, v89
	v_mul_f32_e32 v90, v236, v90
	v_mul_f32_e32 v91, v236, v91
	v_mul_f32_e32 v92, v236, v92
	v_mul_f32_e32 v93, v236, v93
	v_mul_f32_e32 v94, v236, v94
	v_mfma_f32_16x16x32_bf16 v[52:55], v[184:187], v[192:195], v[52:55]
	v_mul_f32_e32 v95, v236, v95
	v_mul_f32_e32 v224, s100, v88
	v_mul_f32_e32 v225, s101, v89
	v_mul_f32_e32 v228, s100, v90
	v_mul_f32_e32 v229, s101, v91
	v_exp_f32_e32 v224, v224
	v_exp_f32_e32 v225, v225
	v_exp_f32_e32 v228, v228
	v_exp_f32_e32 v229, v229
	v_add_f32_e32 v224, 1.0, v224
	v_mfma_f32_16x16x32_bf16 v[44:47], v[176:179], v[200:203], v[44:47]
	v_add_f32_e32 v225, 1.0, v225
	v_add_f32_e32 v228, 1.0, v228
	v_add_f32_e32 v229, 1.0, v229
	v_rcp_f32_e32 v224, v224
	v_rcp_f32_e32 v225, v225
	v_rcp_f32_e32 v228, v228
	v_rcp_f32_e32 v229, v229
	v_nop
	v_mul_f32_e32 v88, v224, v88
	v_mul_f32_e32 v89, v225, v89
	v_mfma_f32_16x16x32_bf16 v[36:39], v[184:187], v[200:203], v[36:39]
	v_mul_f32_e32 v90, v228, v90
	v_mul_f32_e32 v91, v229, v91
	v_mul_f32_e32 v88, v92, v88
	v_mul_f32_e32 v89, v93, v89
	v_mul_f32_e32 v90, v94, v90
	v_mul_f32_e32 v91, v95, v91
	v_mul_f32_e32 v80, v236, v80
	v_mul_f32_e32 v81, v236, v81
	v_mul_f32_e32 v82, v236, v82
	v_mul_f32_e32 v83, v236, v83
	v_mfma_f32_16x16x32_bf16 v[28:31], v[176:179], v[208:211], v[28:31]
	v_mul_f32_e32 v84, v236, v84
	v_mul_f32_e32 v85, v236, v85
	v_mul_f32_e32 v86, v236, v86
	v_mul_f32_e32 v87, v236, v87
	v_mul_f32_e32 v224, s100, v80
	v_mul_f32_e32 v225, s101, v81
	v_mul_f32_e32 v228, s100, v82
	v_mul_f32_e32 v229, s101, v83
	v_exp_f32_e32 v224, v224
	v_exp_f32_e32 v225, v225
	v_mfma_f32_16x16x32_bf16 v[20:23], v[184:187], v[208:211], v[20:23]
	v_exp_f32_e32 v228, v228
	v_exp_f32_e32 v229, v229
	v_add_f32_e32 v224, 1.0, v224
	v_add_f32_e32 v225, 1.0, v225
	v_add_f32_e32 v228, 1.0, v228
	v_add_f32_e32 v229, 1.0, v229
	v_rcp_f32_e32 v224, v224
	v_rcp_f32_e32 v225, v225
	v_rcp_f32_e32 v228, v228
	v_rcp_f32_e32 v229, v229
	v_mfma_f32_16x16x32_bf16 v[12:15], v[176:179], v[216:219], v[12:15]
	v_nop
	v_mul_f32_e32 v80, v224, v80
; __device__ __forceinline__ unsigned cvt_pk_bf16(float lo, float hi) { unsigned r; asm volatile("v_cvt_pk_bf16_f32 %0, %1, %2" : "=v"(r) : "v"(lo), "v"(hi)); return r; }
; __device__ __forceinline__ float siluf_(float x) { return x * sigmoidf_(x); }
; #define PG8_BAR __builtin_amdgcn_s_barrier()
;     __device__ __forceinline__ void operator()(const f32x4 (&acc)[2][2][4][2], const Unit& u, int wr, int wc, int fr, int fq) const {
;     ...
;             for (int m = 0; m < 4; ++m) { const int row = row0 + ai * HALF + m * 16; bf16_t* rowp = O + (size_t)row * ldc + col0; const float rs = rsv[ai][m];
;                 f32x4 v0, v1;
; #pragma unroll
;                 for (int j = 0; j < 4; ++j) { v0[j] = siluf_(acc[ai][0][m][0][j] * rs) * (acc[ai][1][m][0][j] * rs); v1[j] = siluf_(acc[ai][0][m][1][j] * rs) * (acc[ai][1][m][1][j] * rs); }
;                 u32x4 w; w.x = cvt_pk_bf16(v0[0], v0[1]); w.y = cvt_pk_bf16(v0[2], v0[3]); w.z = cvt_pk_bf16(v1[0], v1[1]); w.w = cvt_pk_bf16(v1[2], v1[3]);
;                 *(u32x4*)rowp = w; }
; template <class Epi, bool ALIGN_EPI>
; __device__ __forceinline__ void gemm_phase(LAS unsigned char* lds, const Gemm g, const StaticOrder& S, const Epi& E, const int tid) {
;     ...
;         if constexpr (ALIGN_EPI) { if (wr == 0) PG8_BAR; }
;         { int t2 = tid; asm volatile("" : "+v"(t2)); const int l2 = t2 & 63, w2 = __builtin_amdgcn_readfirstlane(t2 >> 6); E(acc, cur, w2 >> 2, w2 & 3, l2 & 15, l2 >> 4); }
;         if (!has_next) break;
; #pragma unroll
;         for (int a = 0; a < 2; ++a)
; #pragma unroll
;             for (int b = 0; b < 2; ++b)
; #pragma unroll
;                 for (int m = 0; m < 4; ++m)
; #pragma unroll
;                     for (int n = 0; n < 2; ++n) acc[a][b][m][n] = (f32x4){0.f, 0.f, 0.f, 0.f};
;         cur = nxt; cA = nA; cB = nB; ++ui;
;         if constexpr (ALIGN_EPI) { if (wr == 1) PG8_BAR; }
	v_mul_f32_e32 v81, v225, v81
	v_mul_f32_e32 v82, v228, v82
	v_mul_f32_e32 v83, v229, v83
	v_mul_f32_e32 v80, v84, v80
	v_mul_f32_e32 v81, v85, v81
	v_mul_f32_e32 v82, v86, v82
	v_mul_f32_e32 v83, v87, v83
	v_cvt_pk_bf16_f32 v88, v88, v89
	v_mfma_f32_16x16x32_bf16 v[0:3], v[184:187], v[216:219], v[0:3]
	v_cvt_pk_bf16_f32 v89, v90, v91
	v_cvt_pk_bf16_f32 v90, v80, v81
	v_cvt_pk_bf16_f32 v91, v82, v83
	global_store_dwordx4 v[232:233], v[88:91], off
	v_lshl_add_u64 v[232:233], v[232:233], 0, s[98:99]
	v_mul_f32_e32 v72, v237, v72
	v_mul_f32_e32 v73, v237, v73
	v_mul_f32_e32 v74, v237, v74
	v_mul_f32_e32 v75, v237, v75
	v_mul_f32_e32 v76, v237, v76
	v_mfma_f32_16x16x32_bf16 v[60:63], v[180:183], v[196:199], v[60:63]
	v_mul_f32_e32 v77, v237, v77
	v_mul_f32_e32 v78, v237, v78
	v_mul_f32_e32 v79, v237, v79
	v_mul_f32_e32 v224, s100, v72
	v_mul_f32_e32 v225, s101, v73
	v_mul_f32_e32 v228, s100, v74
	v_mul_f32_e32 v229, s101, v75
	v_exp_f32_e32 v224, v224
	v_exp_f32_e32 v225, v225
	v_exp_f32_e32 v228, v228
	v_mfma_f32_16x16x32_bf16 v[52:55], v[188:191], v[196:199], v[52:55]
	v_exp_f32_e32 v229, v229
	v_add_f32_e32 v224, 1.0, v224
	v_add_f32_e32 v225, 1.0, v225
	v_add_f32_e32 v228, 1.0, v228
	v_add_f32_e32 v229, 1.0, v229
	v_rcp_f32_e32 v224, v224
	v_rcp_f32_e32 v225, v225
	v_rcp_f32_e32 v228, v228
	v_rcp_f32_e32 v229, v229
	v_nop
	v_mfma_f32_16x16x32_bf16 v[44:47], v[180:183], v[204:207], v[44:47]
	v_mul_f32_e32 v72, v224, v72
	v_mul_f32_e32 v73, v225, v73
	v_mul_f32_e32 v74, v228, v74
	v_mul_f32_e32 v75, v229, v75
	v_mul_f32_e32 v72, v76, v72
	v_mul_f32_e32 v73, v77, v73
	v_mul_f32_e32 v74, v78, v74
	v_mul_f32_e32 v75, v79, v75
	v_mul_f32_e32 v64, v237, v64
	v_mul_f32_e32 v65, v237, v65
	v_mfma_f32_16x16x32_bf16 v[36:39], v[188:191], v[204:207], v[36:39]
	v_mul_f32_e32 v66, v237, v66
	v_mul_f32_e32 v67, v237, v67
	v_mul_f32_e32 v68, v237, v68
	v_mul_f32_e32 v69, v237, v69
	v_mul_f32_e32 v70, v237, v70
	v_mul_f32_e32 v71, v237, v71
	v_mul_f32_e32 v224, s100, v64
	v_mul_f32_e32 v225, s101, v65
	v_mul_f32_e32 v228, s100, v66
	v_mul_f32_e32 v229, s101, v67
	v_mfma_f32_16x16x32_bf16 v[28:31], v[180:183], v[212:215], v[28:31]
	v_exp_f32_e32 v224, v224
	v_exp_f32_e32 v225, v225
	v_exp_f32_e32 v228, v228
	v_exp_f32_e32 v229, v229
	v_add_f32_e32 v224, 1.0, v224
	v_add_f32_e32 v225, 1.0, v225
	v_add_f32_e32 v228, 1.0, v228
	v_add_f32_e32 v229, 1.0, v229
	v_rcp_f32_e32 v224, v224
	v_rcp_f32_e32 v225, v225
	v_mfma_f32_16x16x32_bf16 v[20:23], v[188:191], v[212:215], v[20:23]
	v_rcp_f32_e32 v228, v228
	v_rcp_f32_e32 v229, v229
	v_nop
	v_mul_f32_e32 v64, v224, v64
	v_mul_f32_e32 v65, v225, v65
	v_mul_f32_e32 v66, v228, v66
	v_mul_f32_e32 v67, v229, v67
	v_mul_f32_e32 v64, v68, v64
	v_mul_f32_e32 v65, v69, v65
	v_mul_f32_e32 v66, v70, v66
	v_mfma_f32_16x16x32_bf16 v[12:15], v[180:183], v[240:243], v[12:15]
	v_mul_f32_e32 v67, v71, v67
	v_cvt_pk_bf16_f32 v72, v72, v73
	v_cvt_pk_bf16_f32 v73, v74, v75
	v_cvt_pk_bf16_f32 v74, v64, v65
	v_cvt_pk_bf16_f32 v75, v66, v67
	global_store_dwordx4 v[232:233], v[72:75], off
	v_lshl_add_u64 v[232:233], v[232:233], 0, s[98:99]
	v_lshl_add_u64 v[232:233], v[232:233], 0, s[98:99]
	v_lshl_add_u64 v[232:233], v[232:233], 0, s[98:99]
	v_lshl_add_u64 v[232:233], v[232:233], 0, s[98:99]
	v_mfma_f32_16x16x32_bf16 v[0:3], v[188:191], v[240:243], v[0:3]
	v_lshl_add_u64 v[232:233], v[232:233], 0, s[98:99]
	s_setprio 0
	s_barrier
	v_lshl_add_u64 v[142:143], v[142:143], 0, s[80:81]
	v_lshl_add_u64 v[144:145], v[144:145], 0, s[80:81]
	s_and_b64 vcc, exec, s[8:9]
	s_cbranch_vccnz .Lgu_notdefer
	s_cmp_lg_u32 s62, s64
	s_cbranch_scc1 .Lgu_notdefer
	s_mov_b32 s101, 1
	s_mov_b32 s63, s61
	s_mov_b32 s64, s62
	v_mov_b64_e32 v[144:145], v[140:141]
	v_mov_b64_e32 v[142:143], v[138:139]
	s_branch .LBB0_300

; __device__ __forceinline__ unsigned cvt_pk_bf16(float lo, float hi) { unsigned r; asm volatile("v_cvt_pk_bf16_f32 %0, %1, %2" : "=v"(r) : "v"(lo), "v"(hi)); return r; }
; __device__ __forceinline__ float gelu_tanh(float x) { const float u = 0.7978845608028654f * (x + 0.044715f * x * x * x); return x * fast_rcp(1.0f + fast_exp2(-2.0f * LOG2E * u)); }
; #define PG8_STAGE(bufoff, gbase, voff) do { _Pragma("unroll") for (int _i = 0; _i < 2; ++_i) \
;         __builtin_amdgcn_global_load_lds((const unsigned*)((const char*)(gbase) + (voff)[_i]), (LAS unsigned*)(lds + (bufoff) + ldsw + _i * 8192), 16, 0, 0); } while (0)
; #define PG8_LDA(dst, b, h) do { _Pragma("unroll") for (int m = 0; m < 4; ++m) _Pragma("unroll") for (int k = 0; k < 2; ++k) dst[m][k] = *(const LAS bf16x8*)(lds + PG8_SA(b, h) + aoff + m * 2048 + k * 1024); } while (0)
; #define PG8_WAIT_V(n) asm volatile("s_waitcnt vmcnt(" #n ")" ::: "memory")
;     __device__ __forceinline__ void operator()(const f32x4 (&acc)[2][2][4][2], const Unit& u, int wr, int wc, int fr, int fq) const {
;         const int row0 = u.pm * BM + wr * 64 + fr, col0 = u.pn * BM + wc * 32 + 8 * fq;
;         float rsv[2][4]; load_rstd(rsv, ssq, row0);
; #pragma unroll
;         for (int ai = 0; ai < 2; ++ai)
; #pragma unroll
;             for (int m = 0; m < 4; ++m) { const int row = row0 + ai * HALF + m * 16; bf16_t* rowp = O + (size_t)row * ldc + col0; const float rs = rsv[ai][m];
; #pragma unroll
;                 for (int bj = 0; bj < 2; ++bj) { f32x4 v0 = acc[ai][bj][m][0] * rs, v1 = acc[ai][bj][m][1] * rs;
;                     if (ACT == 1) {
; #pragma unroll
;                         for (int j = 0; j < 4; ++j) { v0[j] = gelu_tanh(v0[j]); v1[j] = gelu_tanh(v1[j]); } }
;                     u32x4 w; w.x = cvt_pk_bf16(v0[0], v0[1]); w.y = cvt_pk_bf16(v0[2], v0[3]); w.z = cvt_pk_bf16(v1[0], v1[1]); w.w = cvt_pk_bf16(v1[2], v1[3]);
;                     *(u32x4*)(rowp + bj * HALF) = w; } }
; template <class Epi, bool ALIGN_EPI>
; __device__ __forceinline__ void gemm_phase(LAS unsigned char* lds, const Gemm g, const StaticOrder& S, const Epi& E, const int tid) {
;     ...
;             PG8_LDB(B0, 0, 0); PG8_LDB(B1, 0, 1); PG8_SCHED; PG8_LDA(At, 0, 0); PG8_STAGE(PG8_SA(1, 1), a1 + hA, voffA);
;             PG8_WAIT_V(8); PG8_WAIT_L(0); PG8_BAR; PG8_MMA(0, 0, At, B0); PG8_MMA(0, 1, At, B1); PG8_BAR; PG8_SCHED;
.Lq5_first_epi:
	s_add_i32 s11, s10, 2
	s_cmp_eq_u32 s55, s10
	s_cselect_b64 vcc, -1, 0
	v_add_u32_e32 v148, s33, v149
	s_add_i32 s10, 0, 0x14000
	ds_read_b128 v[152:155], v148
	ds_read_b128 v[156:159], v148 offset:1024
	ds_read_b128 v[160:163], v148 offset:2048
	ds_read_b128 v[164:167], v148 offset:3072
	v_add_u32_e32 v148, s10, v149
	ds_read_b128 v[176:179], v148
	ds_read_b128 v[180:183], v148 offset:1024
	ds_read_b128 v[184:187], v148 offset:2048
	ds_read_b128 v[188:191], v148 offset:3072
	v_lshl_add_u64 v[146:147], v[142:143], 0, s[92:93]
	v_cndmask_b32_e32 v147, v147, v139, vcc
	v_cndmask_b32_e32 v146, v146, v138, vcc
	v_cndmask_b32_e32 v221, v145, v141, vcc
	v_cndmask_b32_e32 v220, v144, v140, vcc
	v_lshl_add_u64 v[244:245], v[142:143], 0, v[134:135]
	s_add_i32 m0, s25, 0xc000
	ds_read_b128 v[192:195], v151
	ds_read_b128 v[196:199], v151 offset:1024
	ds_read_b128 v[200:203], v151 offset:2048
	ds_read_b128 v[204:207], v151 offset:3072
	ds_read_b128 v[208:211], v151 offset:4096
	ds_read_b128 v[212:215], v151 offset:5120
	ds_read_b128 v[216:219], v151 offset:6144
	ds_read_b128 v[240:243], v151 offset:7168
	global_load_lds_dwordx4 v[244:245], off
	v_lshl_add_u64 v[244:245], v[142:143], 0, v[136:137]
	s_add_i32 m0, s25, 0xe000
	s_nop 0
	global_load_lds_dwordx4 v[244:245], off
	s_waitcnt vmcnt(16)
	s_waitcnt lgkmcnt(0)
	s_barrier
	s_waitcnt lgkmcnt(0)
	v_mfma_f32_16x16x32_bf16 v[124:127], v[152:155], v[192:195], 0
	s_lshl_b32 s98, s28, 5
	s_mov_b32 s99, 0
	v_mul_f32_e32 v60, v238, v60
	v_mul_f32_e32 v61, v238, v61
	v_mfma_f32_16x16x32_bf16 v[120:123], v[160:163], v[192:195], 0
	v_mul_f32_e32 v62, v238, v62
	v_mul_f32_e32 v63, v238, v63
	v_mul_f32_e32 v56, v238, v56
	v_mul_f32_e32 v57, v238, v57
	v_mfma_f32_16x16x32_bf16 v[108:111], v[152:155], v[200:203], 0
	v_mul_f32_e32 v58, v238, v58
	v_mul_f32_e32 v59, v238, v59
	v_cvt_pk_bf16_f32 v60, v60, v61
	v_cvt_pk_bf16_f32 v61, v62, v63
	v_mfma_f32_16x16x32_bf16 v[104:107], v[160:163], v[200:203], 0
	v_cvt_pk_bf16_f32 v62, v56, v57
	v_cvt_pk_bf16_f32 v63, v58, v59
	global_store_dwordx4 v[232:233], v[60:63], off
	v_mul_f32_e32 v52, v238, v52
	v_mfma_f32_16x16x32_bf16 v[92:95], v[152:155], v[208:211], 0
	v_mul_f32_e32 v53, v238, v53
	v_mul_f32_e32 v54, v238, v54
	v_mul_f32_e32 v55, v238, v55
	v_mul_f32_e32 v48, v238, v48
	v_mfma_f32_16x16x32_bf16 v[88:91], v[160:163], v[208:211], 0
	v_mul_f32_e32 v49, v238, v49
	v_mul_f32_e32 v50, v238, v50
	v_mul_f32_e32 v51, v238, v51
	v_cvt_pk_bf16_f32 v52, v52, v53
	v_mfma_f32_16x16x32_bf16 v[76:79], v[152:155], v[216:219], 0
	v_cvt_pk_bf16_f32 v53, v54, v55
	v_cvt_pk_bf16_f32 v54, v48, v49
	v_cvt_pk_bf16_f32 v55, v50, v51
	global_store_dwordx4 v[232:233], v[52:55], off offset:256
	v_mfma_f32_16x16x32_bf16 v[72:75], v[160:163], v[216:219], 0
	v_lshl_add_u64 v[232:233], v[232:233], 0, s[98:99]
	v_mul_f32_e32 v44, v239, v44
	v_mul_f32_e32 v45, v239, v45
	v_mul_f32_e32 v46, v239, v46
	v_mfma_f32_16x16x32_bf16 v[124:127], v[156:159], v[196:199], v[124:127]
	v_mul_f32_e32 v47, v239, v47
	v_mul_f32_e32 v40, v239, v40
	v_mul_f32_e32 v41, v239, v41
	v_mul_f32_e32 v42, v239, v42
	v_mfma_f32_16x16x32_bf16 v[120:123], v[164:167], v[196:199], v[120:123]
	v_mul_f32_e32 v43, v239, v43
	v_cvt_pk_bf16_f32 v44, v44, v45
	v_cvt_pk_bf16_f32 v45, v46, v47
	v_cvt_pk_bf16_f32 v46, v40, v41
	v_mfma_f32_16x16x32_bf16 v[108:111], v[156:159], v[204:207], v[108:111]
	v_cvt_pk_bf16_f32 v47, v42, v43
	global_store_dwordx4 v[232:233], v[44:47], off
	v_mul_f32_e32 v36, v239, v36
	v_mul_f32_e32 v37, v239, v37
	v_mfma_f32_16x16x32_bf16 v[104:107], v[164:167], v[204:207], v[104:107]
	v_mul_f32_e32 v38, v239, v38
	v_mul_f32_e32 v39, v239, v39
	v_mul_f32_e32 v32, v239, v32
	v_mul_f32_e32 v33, v239, v33
	v_mfma_f32_16x16x32_bf16 v[92:95], v[156:159], v[212:215], v[92:95]
	v_mul_f32_e32 v34, v239, v34
	v_mul_f32_e32 v35, v239, v35
	v_cvt_pk_bf16_f32 v36, v36, v37
	v_cvt_pk_bf16_f32 v37, v38, v39
	v_mfma_f32_16x16x32_bf16 v[88:91], v[164:167], v[212:215], v[88:91]
	v_cvt_pk_bf16_f32 v38, v32, v33
	v_cvt_pk_bf16_f32 v39, v34, v35
	global_store_dwordx4 v[232:233], v[36:39], off offset:256
	v_lshl_add_u64 v[232:233], v[232:233], 0, s[98:99]
	v_mfma_f32_16x16x32_bf16 v[76:79], v[156:159], v[240:243], v[76:79]
	v_mul_f32_e32 v28, v230, v28
	v_mul_f32_e32 v29, v230, v29
	v_mul_f32_e32 v30, v230, v30
	v_mul_f32_e32 v31, v230, v31
	v_mfma_f32_16x16x32_bf16 v[72:75], v[164:167], v[240:243], v[72:75]
	v_mul_f32_e32 v24, v230, v24
	v_mul_f32_e32 v25, v230, v25
	v_mul_f32_e32 v26, v230, v26
	v_mul_f32_e32 v27, v230, v27
	s_setprio 0
	v_mfma_f32_16x16x32_bf16 v[116:119], v[176:179], v[192:195], 0
	v_cvt_pk_bf16_f32 v28, v28, v29
	v_cvt_pk_bf16_f32 v29, v30, v31
	v_cvt_pk_bf16_f32 v30, v24, v25
	v_cvt_pk_bf16_f32 v31, v26, v27
	v_mfma_f32_16x16x32_bf16 v[112:115], v[184:187], v[192:195], 0
	global_store_dwordx4 v[232:233], v[28:31], off
	v_mul_f32_e32 v20, v230, v20
	v_mul_f32_e32 v21, v230, v21
	v_mul_f32_e32 v22, v230, v22
	v_mfma_f32_16x16x32_bf16 v[100:103], v[176:179], v[200:203], 0
	v_mul_f32_e32 v23, v230, v23
	v_mul_f32_e32 v16, v230, v16
	v_mul_f32_e32 v17, v230, v17
	v_mul_f32_e32 v18, v230, v18
	v_mfma_f32_16x16x32_bf16 v[96:99], v[184:187], v[200:203], 0
	v_mul_f32_e32 v19, v230, v19
	v_cvt_pk_bf16_f32 v20, v20, v21
	v_cvt_pk_bf16_f32 v21, v22, v23
	v_cvt_pk_bf16_f32 v22, v16, v17
	v_mfma_f32_16x16x32_bf16 v[84:87], v[176:179], v[208:211], 0
	v_cvt_pk_bf16_f32 v23, v18, v19
	global_store_dwordx4 v[232:233], v[20:23], off offset:256
	v_lshl_add_u64 v[232:233], v[232:233], 0, s[98:99]
	v_mul_f32_e32 v12, v231, v12
	v_mfma_f32_16x16x32_bf16 v[80:83], v[184:187], v[208:211], 0
	v_mul_f32_e32 v13, v231, v13
; #define PG8_STAGE(bufoff, gbase, voff) do { _Pragma("unroll") for (int _i = 0; _i < 2; ++_i) \
;         __builtin_amdgcn_global_load_lds((const unsigned*)((const char*)(gbase) + (voff)[_i]), (LAS unsigned*)(lds + (bufoff) + ldsw + _i * 8192), 16, 0, 0); } while (0)
; #define PG8_LDA(dst, b, h) do { _Pragma("unroll") for (int m = 0; m < 4; ++m) _Pragma("unroll") for (int k = 0; k < 2; ++k) dst[m][k] = *(const LAS bf16x8*)(lds + PG8_SA(b, h) + aoff + m * 2048 + k * 1024); } while (0)
; #define PG8_LDB(dst, b, h) do { _Pragma("unroll") for (int n = 0; n < 2; ++n) _Pragma("unroll") for (int k = 0; k < 2; ++k) dst[n][k] = *(const LAS bf16x8*)(lds + PG8_SB(b, h) + boff + n * 2048 + k * 1024); } while (0)
; #define PG8_MMA(ai, bj, At, Bt) do { __builtin_amdgcn_s_setprio(1); _Pragma("unroll") for (int k = 0; k < 2; ++k) _Pragma("unroll") for (int m = 0; m < 4; ++m) _Pragma("unroll") for (int n = 0; n < 2; ++n) \
;         acc[ai][bj][m][n] = __builtin_amdgcn_mfma_f32_16x16x32_bf16(Bt[n][k], At[m][k], acc[ai][bj][m][n], 0, 0, 0); __builtin_amdgcn_s_setprio(0); } while (0)
; #define PG8_WAIT_V(n) asm volatile("s_waitcnt vmcnt(" #n ")" ::: "memory")
; #define PG8_WAIT_L(n) asm volatile("s_waitcnt lgkmcnt(" #n ")" ::: "memory")
; #define PG8_BAR __builtin_amdgcn_s_barrier()
; #define PG8_SCHED __builtin_amdgcn_sched_barrier(0)
; template <class Epi, bool ALIGN_EPI>
; __device__ __forceinline__ void gemm_phase(LAS unsigned char* lds, const Gemm g, const StaticOrder& S, const Epi& E, const int tid) {
;     ...
;             PG8_WAIT_V(8); PG8_WAIT_L(0); PG8_BAR; PG8_MMA(0, 0, At, B0); PG8_MMA(0, 1, At, B1); PG8_BAR; PG8_SCHED;
;             PG8_LDA(At, 0, 1); PG8_STAGE(PG8_SB(0, 0), b2, voffB); PG8_STAGE(PG8_SB(0, 1), b2 + hB, voffB); PG8_STAGE(PG8_SA(0, 0), a2, voffA);
;             PG8_WAIT_V(8); PG8_WAIT_L(0); PG8_BAR; PG8_MMA(1, 0, At, B0); PG8_MMA(1, 1, At, B1); PG8_BAR; PG8_SCHED;
;             PG8_LDB(B0, 1, 0); PG8_LDB(B1, 1, 1); PG8_SCHED; PG8_LDA(At, 1, 0); PG8_STAGE(PG8_SA(0, 1), a2 + hA, voffA);
	v_mul_f32_e32 v14, v231, v14
	v_mul_f32_e32 v15, v231, v15
	v_mul_f32_e32 v8, v231, v8
	v_mfma_f32_16x16x32_bf16 v[68:71], v[176:179], v[216:219], 0
	v_mul_f32_e32 v9, v231, v9
	v_mul_f32_e32 v10, v231, v10
	v_mul_f32_e32 v11, v231, v11
	v_cvt_pk_bf16_f32 v12, v12, v13
	v_mfma_f32_16x16x32_bf16 v[64:67], v[184:187], v[216:219], 0
	v_cvt_pk_bf16_f32 v13, v14, v15
	v_cvt_pk_bf16_f32 v14, v8, v9
	v_cvt_pk_bf16_f32 v15, v10, v11
	global_store_dwordx4 v[232:233], v[12:15], off
	v_mfma_f32_16x16x32_bf16 v[116:119], v[180:183], v[196:199], v[116:119]
	v_mul_f32_e32 v4, v231, v4
	v_mul_f32_e32 v5, v231, v5
	v_mul_f32_e32 v6, v231, v6
	v_mul_f32_e32 v7, v231, v7
	v_mfma_f32_16x16x32_bf16 v[112:115], v[188:191], v[196:199], v[112:115]
	v_mul_f32_e32 v0, v231, v0
	v_mul_f32_e32 v1, v231, v1
	v_mul_f32_e32 v2, v231, v2
	v_mul_f32_e32 v3, v231, v3
	v_mfma_f32_16x16x32_bf16 v[100:103], v[180:183], v[204:207], v[100:103]
	v_cvt_pk_bf16_f32 v4, v4, v5
	v_cvt_pk_bf16_f32 v5, v6, v7
	v_cvt_pk_bf16_f32 v6, v0, v1
	v_cvt_pk_bf16_f32 v7, v2, v3
	v_mfma_f32_16x16x32_bf16 v[96:99], v[188:191], v[204:207], v[96:99]
	global_store_dwordx4 v[232:233], v[4:7], off offset:256
	v_mfma_f32_16x16x32_bf16 v[84:87], v[180:183], v[212:215], v[84:87]
	v_mfma_f32_16x16x32_bf16 v[80:83], v[188:191], v[212:215], v[80:83]
	v_mfma_f32_16x16x32_bf16 v[68:71], v[180:183], v[240:243], v[68:71]
	v_mfma_f32_16x16x32_bf16 v[64:67], v[188:191], v[240:243], v[64:67]
	s_setprio 0
	s_barrier
	s_add_i32 s62, s33, s45
	v_lshl_add_u64 v[244:245], v[220:221], 0, v[168:169]
	s_mov_b32 m0, s62
	ds_read_b128 v[192:195], v151 offset:16384
	ds_read_b128 v[196:199], v151 offset:17408
	ds_read_b128 v[200:203], v151 offset:18432
	ds_read_b128 v[204:207], v151 offset:19456
	ds_read_b128 v[208:211], v151 offset:20480
	ds_read_b128 v[212:215], v151 offset:21504
	ds_read_b128 v[216:219], v151 offset:22528
	ds_read_b128 v[240:243], v151 offset:23552
	global_load_lds_dwordx4 v[244:245], off
	v_lshl_add_u64 v[246:247], v[220:221], 0, v[128:129]
	s_add_i32 m0, s62, 0x2000
	v_lshl_add_u64 v[220:221], v[220:221], 0, s[12:13]
	s_add_i32 s10, s10, s45
	global_load_lds_dwordx4 v[246:247], off
	v_lshl_add_u64 v[248:249], v[220:221], 0, v[168:169]
	s_mov_b32 m0, s10
	v_lshl_add_u64 v[220:221], v[220:221], 0, v[128:129]
	global_load_lds_dwordx4 v[248:249], off
	s_add_i32 m0, s10, 0x2000
	v_lshl_add_u64 v[250:251], v[146:147], 0, v[132:133]
	global_load_lds_dwordx4 v[220:221], off
	s_mov_b32 m0, s25
	v_lshl_add_u64 v[252:253], v[146:147], 0, v[130:131]
	global_load_lds_dwordx4 v[250:251], off
	s_mov_b32 m0, s50
	s_nop 0
	global_load_lds_dwordx4 v[252:253], off
	s_waitcnt vmcnt(24)
	s_waitcnt lgkmcnt(0)
	s_barrier
	s_setprio 1
	s_waitcnt lgkmcnt(0)
	v_mfma_f32_16x16x32_bf16 v[60:63], v[152:155], v[192:195], 0
	v_mfma_f32_16x16x32_bf16 v[56:59], v[160:163], v[192:195], 0
	v_mfma_f32_16x16x32_bf16 v[44:47], v[152:155], v[200:203], 0
	v_mfma_f32_16x16x32_bf16 v[40:43], v[160:163], v[200:203], 0
	v_mfma_f32_16x16x32_bf16 v[28:31], v[152:155], v[208:211], 0
	v_mfma_f32_16x16x32_bf16 v[24:27], v[160:163], v[208:211], 0
	v_mfma_f32_16x16x32_bf16 v[12:15], v[152:155], v[216:219], 0
	v_mfma_f32_16x16x32_bf16 v[8:11], v[160:163], v[216:219], 0
	v_mfma_f32_16x16x32_bf16 v[60:63], v[156:159], v[196:199], v[60:63]
	v_mfma_f32_16x16x32_bf16 v[56:59], v[164:167], v[196:199], v[56:59]
	v_mfma_f32_16x16x32_bf16 v[44:47], v[156:159], v[204:207], v[44:47]
	v_mfma_f32_16x16x32_bf16 v[40:43], v[164:167], v[204:207], v[40:43]
	v_mfma_f32_16x16x32_bf16 v[28:31], v[156:159], v[212:215], v[28:31]
	v_mfma_f32_16x16x32_bf16 v[24:27], v[164:167], v[212:215], v[24:27]
	v_mfma_f32_16x16x32_bf16 v[12:15], v[156:159], v[240:243], v[12:15]
	v_mfma_f32_16x16x32_bf16 v[8:11], v[164:167], v[240:243], v[8:11]
	s_setprio 0
	s_setprio 1
	v_mfma_f32_16x16x32_bf16 v[52:55], v[176:179], v[192:195], 0
	v_mfma_f32_16x16x32_bf16 v[48:51], v[184:187], v[192:195], 0
	v_mfma_f32_16x16x32_bf16 v[36:39], v[176:179], v[200:203], 0
	v_mfma_f32_16x16x32_bf16 v[32:35], v[184:187], v[200:203], 0
	v_mfma_f32_16x16x32_bf16 v[20:23], v[176:179], v[208:211], 0
	v_mfma_f32_16x16x32_bf16 v[16:19], v[184:187], v[208:211], 0
	v_mfma_f32_16x16x32_bf16 v[4:7], v[176:179], v[216:219], 0
	v_mfma_f32_16x16x32_bf16 v[0:3], v[184:187], v[216:219], 0
	v_mfma_f32_16x16x32_bf16 v[52:55], v[180:183], v[196:199], v[52:55]
	v_mfma_f32_16x16x32_bf16 v[48:51], v[188:191], v[196:199], v[48:51]
	v_mfma_f32_16x16x32_bf16 v[36:39], v[180:183], v[204:207], v[36:39]
	v_mfma_f32_16x16x32_bf16 v[32:35], v[188:191], v[204:207], v[32:35]
	v_mfma_f32_16x16x32_bf16 v[20:23], v[180:183], v[212:215], v[20:23]
	v_mfma_f32_16x16x32_bf16 v[16:19], v[188:191], v[212:215], v[16:19]
	v_mfma_f32_16x16x32_bf16 v[4:7], v[180:183], v[240:243], v[4:7]
	v_mfma_f32_16x16x32_bf16 v[0:3], v[188:191], v[240:243], v[0:3]
	s_setprio 0
	s_barrier
	s_add_i32 s10, 0, 0x18000
	v_add_u32_e32 v148, s10, v149
	s_add_i32 s62, 0, 0x1c000
	ds_read_b128 v[152:155], v148
	ds_read_b128 v[156:159], v148 offset:1024
	ds_read_b128 v[160:163], v148 offset:2048
	ds_read_b128 v[164:167], v148 offset:3072
	v_add_u32_e32 v148, s62, v149
	ds_read_b128 v[176:179], v148
	ds_read_b128 v[180:183], v148 offset:1024
	ds_read_b128 v[184:187], v148 offset:2048
	ds_read_b128 v[188:191], v148 offset:3072
	v_lshl_add_u64 v[146:147], v[146:147], 0, s[94:95]
	s_mov_b32 m0, s51
	v_lshl_add_u64 v[226:227], v[146:147], 0, v[132:133]
	ds_read_b128 v[192:195], v151 offset:32768
	ds_read_b128 v[196:199], v151 offset:33792
	ds_read_b128 v[200:203], v151 offset:34816
	ds_read_b128 v[204:207], v151 offset:35840
	ds_read_b128 v[208:211], v151 offset:36864
	ds_read_b128 v[212:215], v151 offset:37888
	ds_read_b128 v[216:219], v151 offset:38912
	ds_read_b128 v[240:243], v151 offset:39936
	global_load_lds_dwordx4 v[226:227], off
	v_lshl_add_u64 v[146:147], v[146:147], 0, v[130:131]
	s_mov_b32 m0, s52
	s_nop 0
	global_load_lds_dwordx4 v[146:147], off
	s_waitcnt vmcnt(16)
	s_waitcnt lgkmcnt(0)
	s_barrier
; #define PG8_STAGE(bufoff, gbase, voff) do { _Pragma("unroll") for (int _i = 0; _i < 2; ++_i) \
;         __builtin_amdgcn_global_load_lds((const unsigned*)((const char*)(gbase) + (voff)[_i]), (LAS unsigned*)(lds + (bufoff) + ldsw + _i * 8192), 16, 0, 0); } while (0)
; #define PG8_LDA(dst, b, h) do { _Pragma("unroll") for (int m = 0; m < 4; ++m) _Pragma("unroll") for (int k = 0; k < 2; ++k) dst[m][k] = *(const LAS bf16x8*)(lds + PG8_SA(b, h) + aoff + m * 2048 + k * 1024); } while (0)
; #define PG8_MMA(ai, bj, At, Bt) do { __builtin_amdgcn_s_setprio(1); _Pragma("unroll") for (int k = 0; k < 2; ++k) _Pragma("unroll") for (int m = 0; m < 4; ++m) _Pragma("unroll") for (int n = 0; n < 2; ++n) \
;         acc[ai][bj][m][n] = __builtin_amdgcn_mfma_f32_16x16x32_bf16(Bt[n][k], At[m][k], acc[ai][bj][m][n], 0, 0, 0); __builtin_amdgcn_s_setprio(0); } while (0)
; #define PG8_WAIT_V(n) asm volatile("s_waitcnt vmcnt(" #n ")" ::: "memory")
; #define PG8_WAIT_L(n) asm volatile("s_waitcnt lgkmcnt(" #n ")" ::: "memory")
; #define PG8_BAR __builtin_amdgcn_s_barrier()
; #define PG8_SCHED __builtin_amdgcn_sched_barrier(0)
; template <class Epi, bool ALIGN_EPI>
; __device__ __forceinline__ void gemm_phase(LAS unsigned char* lds, const Gemm g, const StaticOrder& S, const Epi& E, const int tid) {
;     ...
;         for (int t = 0; t < nt; t += 2) {
;     ...
;             PG8_WAIT_V(8); PG8_WAIT_L(0); PG8_BAR; PG8_MMA(0, 0, At, B0); PG8_MMA(0, 1, At, B1); PG8_BAR; PG8_SCHED;
;             PG8_LDA(At, 1, 1); PG8_STAGE(PG8_SB(1, 0), b3, voffB); PG8_STAGE(PG8_SB(1, 1), b3 + hB, voffB); PG8_STAGE(PG8_SA(1, 0), a3, voffA);
;             PG8_WAIT_V(8); PG8_WAIT_L(0); PG8_BAR; PG8_MMA(1, 0, At, B0); PG8_MMA(1, 1, At, B1); PG8_BAR; PG8_SCHED;
;         }
	s_setprio 1
	s_waitcnt lgkmcnt(0)
	v_mfma_f32_16x16x32_bf16 v[124:127], v[152:155], v[192:195], v[124:127]
	v_mfma_f32_16x16x32_bf16 v[120:123], v[160:163], v[192:195], v[120:123]
	v_mfma_f32_16x16x32_bf16 v[108:111], v[152:155], v[200:203], v[108:111]
	v_mfma_f32_16x16x32_bf16 v[104:107], v[160:163], v[200:203], v[104:107]
	v_mfma_f32_16x16x32_bf16 v[92:95], v[152:155], v[208:211], v[92:95]
	v_mfma_f32_16x16x32_bf16 v[88:91], v[160:163], v[208:211], v[88:91]
	v_mfma_f32_16x16x32_bf16 v[76:79], v[152:155], v[216:219], v[76:79]
	v_mfma_f32_16x16x32_bf16 v[72:75], v[160:163], v[216:219], v[72:75]
	v_mfma_f32_16x16x32_bf16 v[124:127], v[156:159], v[196:199], v[124:127]
	v_mfma_f32_16x16x32_bf16 v[120:123], v[164:167], v[196:199], v[120:123]
	v_mfma_f32_16x16x32_bf16 v[108:111], v[156:159], v[204:207], v[108:111]
	v_mfma_f32_16x16x32_bf16 v[104:107], v[164:167], v[204:207], v[104:107]
	v_mfma_f32_16x16x32_bf16 v[92:95], v[156:159], v[212:215], v[92:95]
	v_mfma_f32_16x16x32_bf16 v[88:91], v[164:167], v[212:215], v[88:91]
	v_mfma_f32_16x16x32_bf16 v[76:79], v[156:159], v[240:243], v[76:79]
	v_mfma_f32_16x16x32_bf16 v[72:75], v[164:167], v[240:243], v[72:75]
	s_setprio 0
	s_setprio 1
	v_mfma_f32_16x16x32_bf16 v[116:119], v[176:179], v[192:195], v[116:119]
	v_mfma_f32_16x16x32_bf16 v[112:115], v[184:187], v[192:195], v[112:115]
	v_mfma_f32_16x16x32_bf16 v[100:103], v[176:179], v[200:203], v[100:103]
	v_mfma_f32_16x16x32_bf16 v[96:99], v[184:187], v[200:203], v[96:99]
	v_mfma_f32_16x16x32_bf16 v[84:87], v[176:179], v[208:211], v[84:87]
	v_mfma_f32_16x16x32_bf16 v[80:83], v[184:187], v[208:211], v[80:83]
	v_mfma_f32_16x16x32_bf16 v[68:71], v[176:179], v[216:219], v[68:71]
	v_mfma_f32_16x16x32_bf16 v[64:67], v[184:187], v[216:219], v[64:67]
	v_mfma_f32_16x16x32_bf16 v[116:119], v[180:183], v[196:199], v[116:119]
	v_mfma_f32_16x16x32_bf16 v[112:115], v[188:191], v[196:199], v[112:115]
	v_mfma_f32_16x16x32_bf16 v[100:103], v[180:183], v[204:207], v[100:103]
	v_mfma_f32_16x16x32_bf16 v[96:99], v[188:191], v[204:207], v[96:99]
	v_mfma_f32_16x16x32_bf16 v[84:87], v[180:183], v[212:215], v[84:87]
	v_mfma_f32_16x16x32_bf16 v[80:83], v[188:191], v[212:215], v[80:83]
	v_mfma_f32_16x16x32_bf16 v[68:71], v[180:183], v[240:243], v[68:71]
	v_mfma_f32_16x16x32_bf16 v[64:67], v[188:191], v[240:243], v[64:67]
	s_setprio 0
	s_barrier
	s_add_i32 s10, s10, s45
	v_lshl_add_u64 v[146:147], v[244:245], 0, s[92:93]
	s_mov_b32 m0, s10
	ds_read_b128 v[192:195], v151 offset:49152
	ds_read_b128 v[196:199], v151 offset:50176
	ds_read_b128 v[200:203], v151 offset:51200
	ds_read_b128 v[204:207], v151 offset:52224
	ds_read_b128 v[208:211], v151 offset:53248
	ds_read_b128 v[212:215], v151 offset:54272
	ds_read_b128 v[216:219], v151 offset:55296
	ds_read_b128 v[240:243], v151 offset:56320
	global_load_lds_dwordx4 v[146:147], off
	v_lshl_add_u64 v[146:147], v[246:247], 0, s[92:93]
	s_add_i32 m0, s10, 0x2000
	s_add_i32 s10, s62, s45
	global_load_lds_dwordx4 v[146:147], off
	v_lshl_add_u64 v[146:147], v[248:249], 0, s[92:93]
	s_mov_b32 m0, s10
	s_nop 0
	global_load_lds_dwordx4 v[146:147], off
	v_lshl_add_u64 v[146:147], v[220:221], 0, s[92:93]
	s_add_i32 m0, s10, 0x2000
	s_nop 0
	global_load_lds_dwordx4 v[146:147], off
	v_lshl_add_u64 v[146:147], v[250:251], 0, s[92:93]
	s_mov_b32 m0, s53
	s_nop 0
	global_load_lds_dwordx4 v[146:147], off
	v_lshl_add_u64 v[146:147], v[252:253], 0, s[92:93]
	s_mov_b32 m0, s54
	s_nop 0
	global_load_lds_dwordx4 v[146:147], off
	s_waitcnt vmcnt(8)
	s_waitcnt lgkmcnt(0)
	s_barrier
	s_setprio 1
	s_waitcnt lgkmcnt(0)
	v_mfma_f32_16x16x32_bf16 v[60:63], v[152:155], v[192:195], v[60:63]
	v_mfma_f32_16x16x32_bf16 v[56:59], v[160:163], v[192:195], v[56:59]
	v_mfma_f32_16x16x32_bf16 v[44:47], v[152:155], v[200:203], v[44:47]
	v_mfma_f32_16x16x32_bf16 v[40:43], v[160:163], v[200:203], v[40:43]
	v_mfma_f32_16x16x32_bf16 v[28:31], v[152:155], v[208:211], v[28:31]
	v_mfma_f32_16x16x32_bf16 v[24:27], v[160:163], v[208:211], v[24:27]
	v_mfma_f32_16x16x32_bf16 v[12:15], v[152:155], v[216:219], v[12:15]
	v_mfma_f32_16x16x32_bf16 v[8:11], v[160:163], v[216:219], v[8:11]
	v_mfma_f32_16x16x32_bf16 v[60:63], v[156:159], v[196:199], v[60:63]
	v_mfma_f32_16x16x32_bf16 v[56:59], v[164:167], v[196:199], v[56:59]
	v_mfma_f32_16x16x32_bf16 v[44:47], v[156:159], v[204:207], v[44:47]
	v_mfma_f32_16x16x32_bf16 v[40:43], v[164:167], v[204:207], v[40:43]
	v_mfma_f32_16x16x32_bf16 v[28:31], v[156:159], v[212:215], v[28:31]
	v_mfma_f32_16x16x32_bf16 v[24:27], v[164:167], v[212:215], v[24:27]
	v_mfma_f32_16x16x32_bf16 v[12:15], v[156:159], v[240:243], v[12:15]
	v_mfma_f32_16x16x32_bf16 v[8:11], v[164:167], v[240:243], v[8:11]
	s_setprio 0
	s_setprio 1
	v_mfma_f32_16x16x32_bf16 v[52:55], v[176:179], v[192:195], v[52:55]
	v_mfma_f32_16x16x32_bf16 v[48:51], v[184:187], v[192:195], v[48:51]
	v_mfma_f32_16x16x32_bf16 v[36:39], v[176:179], v[200:203], v[36:39]
	v_mfma_f32_16x16x32_bf16 v[32:35], v[184:187], v[200:203], v[32:35]
	v_mfma_f32_16x16x32_bf16 v[20:23], v[176:179], v[208:211], v[20:23]
	v_mfma_f32_16x16x32_bf16 v[16:19], v[184:187], v[208:211], v[16:19]
	v_mfma_f32_16x16x32_bf16 v[4:7], v[176:179], v[216:219], v[4:7]
	v_mfma_f32_16x16x32_bf16 v[0:3], v[184:187], v[216:219], v[0:3]
	v_mfma_f32_16x16x32_bf16 v[52:55], v[180:183], v[196:199], v[52:55]
	v_mfma_f32_16x16x32_bf16 v[48:51], v[188:191], v[196:199], v[48:51]
	v_mfma_f32_16x16x32_bf16 v[36:39], v[180:183], v[204:207], v[36:39]
	v_mfma_f32_16x16x32_bf16 v[32:35], v[188:191], v[204:207], v[32:35]
	v_mfma_f32_16x16x32_bf16 v[20:23], v[180:183], v[212:215], v[20:23]
	v_mfma_f32_16x16x32_bf16 v[16:19], v[188:191], v[212:215], v[16:19]
	v_mfma_f32_16x16x32_bf16 v[4:7], v[180:183], v[240:243], v[4:7]
	v_mfma_f32_16x16x32_bf16 v[0:3], v[188:191], v[240:243], v[0:3]
	s_setprio 0
	s_barrier
	v_lshl_add_u64 v[142:143], v[142:143], 0, s[80:81]
	v_lshl_add_u64 v[144:145], v[144:145], 0, s[80:81]
	s_mov_b32 s10, s11
	s_cmp_eq_u32 s10, s55
	s_cbranch_scc1 .Lq5_last
	s_branch .LBB0_354

; #define PG8_STAGE(bufoff, gbase, voff) do { _Pragma("unroll") for (int _i = 0; _i < 2; ++_i) \
;         __builtin_amdgcn_global_load_lds((const unsigned*)((const char*)(gbase) + (voff)[_i]), (LAS unsigned*)(lds + (bufoff) + ldsw + _i * 8192), 16, 0, 0); } while (0)
; #define PG8_LDA(dst, b, h) do { _Pragma("unroll") for (int m = 0; m < 4; ++m) _Pragma("unroll") for (int k = 0; k < 2; ++k) dst[m][k] = *(const LAS bf16x8*)(lds + PG8_SA(b, h) + aoff + m * 2048 + k * 1024); } while (0)
; #define PG8_LDB(dst, b, h) do { _Pragma("unroll") for (int n = 0; n < 2; ++n) _Pragma("unroll") for (int k = 0; k < 2; ++k) dst[n][k] = *(const LAS bf16x8*)(lds + PG8_SB(b, h) + boff + n * 2048 + k * 1024); } while (0)
; #define PG8_MMA(ai, bj, At, Bt) do { __builtin_amdgcn_s_setprio(1); _Pragma("unroll") for (int k = 0; k < 2; ++k) _Pragma("unroll") for (int m = 0; m < 4; ++m) _Pragma("unroll") for (int n = 0; n < 2; ++n) \
;         acc[ai][bj][m][n] = __builtin_amdgcn_mfma_f32_16x16x32_bf16(Bt[n][k], At[m][k], acc[ai][bj][m][n], 0, 0, 0); __builtin_amdgcn_s_setprio(0); } while (0)
; #define PG8_WAIT_V(n) asm volatile("s_waitcnt vmcnt(" #n ")" ::: "memory")
; #define PG8_WAIT_L(n) asm volatile("s_waitcnt lgkmcnt(" #n ")" ::: "memory")
; #define PG8_BAR __builtin_amdgcn_s_barrier()
; #define PG8_SCHED __builtin_amdgcn_sched_barrier(0)
; template <class Epi, bool ALIGN_EPI>
; __device__ __forceinline__ void gemm_phase(LAS unsigned char* lds, const Gemm g, const StaticOrder& S, const Epi& E, const int tid) {
;     ...
;             PG8_LDB(B0, 0, 0); PG8_LDB(B1, 0, 1); PG8_SCHED; PG8_LDA(At, 0, 0); PG8_STAGE(PG8_SA(1, 1), a1 + hA, voffA);
;             PG8_WAIT_V(8); PG8_WAIT_L(0); PG8_BAR; PG8_MMA(0, 0, At, B0); PG8_MMA(0, 1, At, B1); PG8_BAR; PG8_SCHED;
;             PG8_LDA(At, 0, 1); PG8_STAGE(PG8_SB(0, 0), b2, voffB); PG8_STAGE(PG8_SB(0, 1), b2 + hB, voffB); PG8_STAGE(PG8_SA(0, 0), a2, voffA);
.Lq5_last:
	s_add_i32 s11, s10, 2
	s_cmp_eq_u32 s55, s10
	s_cselect_b64 vcc, -1, 0
	v_add_u32_e32 v148, s33, v149
	s_add_i32 s10, 0, 0x14000
	ds_read_b128 v[152:155], v148
	ds_read_b128 v[156:159], v148 offset:1024
	ds_read_b128 v[160:163], v148 offset:2048
	ds_read_b128 v[164:167], v148 offset:3072
	v_add_u32_e32 v148, s10, v149
	ds_read_b128 v[176:179], v148
	ds_read_b128 v[180:183], v148 offset:1024
	ds_read_b128 v[184:187], v148 offset:2048
	ds_read_b128 v[188:191], v148 offset:3072
	v_lshl_add_u64 v[146:147], v[142:143], 0, s[92:93]
	v_cndmask_b32_e32 v147, v147, v139, vcc
	v_cndmask_b32_e32 v146, v146, v138, vcc
	v_cndmask_b32_e32 v221, v145, v141, vcc
	v_cndmask_b32_e32 v220, v144, v140, vcc
	v_lshl_add_u64 v[244:245], v[142:143], 0, v[134:135]
	s_add_i32 m0, s25, 0xc000
	ds_read_b128 v[192:195], v151
	ds_read_b128 v[196:199], v151 offset:1024
	ds_read_b128 v[200:203], v151 offset:2048
	ds_read_b128 v[204:207], v151 offset:3072
	ds_read_b128 v[208:211], v151 offset:4096
	ds_read_b128 v[212:215], v151 offset:5120
	ds_read_b128 v[216:219], v151 offset:6144
	ds_read_b128 v[240:243], v151 offset:7168
	global_load_lds_dwordx4 v[244:245], off
	v_lshl_add_u64 v[244:245], v[142:143], 0, v[136:137]
	s_add_i32 m0, s25, 0xe000
	s_nop 0
	global_load_lds_dwordx4 v[244:245], off
	s_waitcnt vmcnt(8)
	s_waitcnt lgkmcnt(0)
	s_barrier
	s_setprio 1
	s_waitcnt lgkmcnt(0)
	v_mfma_f32_16x16x32_bf16 v[124:127], v[152:155], v[192:195], v[124:127]
	v_mfma_f32_16x16x32_bf16 v[120:123], v[160:163], v[192:195], v[120:123]
	v_mfma_f32_16x16x32_bf16 v[108:111], v[152:155], v[200:203], v[108:111]
	v_mfma_f32_16x16x32_bf16 v[104:107], v[160:163], v[200:203], v[104:107]
	v_mfma_f32_16x16x32_bf16 v[92:95], v[152:155], v[208:211], v[92:95]
	v_mfma_f32_16x16x32_bf16 v[88:91], v[160:163], v[208:211], v[88:91]
	v_mfma_f32_16x16x32_bf16 v[76:79], v[152:155], v[216:219], v[76:79]
	v_mfma_f32_16x16x32_bf16 v[72:75], v[160:163], v[216:219], v[72:75]
	v_mfma_f32_16x16x32_bf16 v[124:127], v[156:159], v[196:199], v[124:127]
	v_mfma_f32_16x16x32_bf16 v[120:123], v[164:167], v[196:199], v[120:123]
	v_mfma_f32_16x16x32_bf16 v[108:111], v[156:159], v[204:207], v[108:111]
	v_mfma_f32_16x16x32_bf16 v[104:107], v[164:167], v[204:207], v[104:107]
	v_mfma_f32_16x16x32_bf16 v[92:95], v[156:159], v[212:215], v[92:95]
	v_mfma_f32_16x16x32_bf16 v[88:91], v[164:167], v[212:215], v[88:91]
	v_mfma_f32_16x16x32_bf16 v[76:79], v[156:159], v[240:243], v[76:79]
	v_mfma_f32_16x16x32_bf16 v[72:75], v[164:167], v[240:243], v[72:75]
	s_setprio 0
	s_setprio 1
	v_mfma_f32_16x16x32_bf16 v[116:119], v[176:179], v[192:195], v[116:119]
	v_mfma_f32_16x16x32_bf16 v[112:115], v[184:187], v[192:195], v[112:115]
	v_mfma_f32_16x16x32_bf16 v[100:103], v[176:179], v[200:203], v[100:103]
	v_mfma_f32_16x16x32_bf16 v[96:99], v[184:187], v[200:203], v[96:99]
	v_mfma_f32_16x16x32_bf16 v[84:87], v[176:179], v[208:211], v[84:87]
	v_mfma_f32_16x16x32_bf16 v[80:83], v[184:187], v[208:211], v[80:83]
	v_mfma_f32_16x16x32_bf16 v[68:71], v[176:179], v[216:219], v[68:71]
	v_mfma_f32_16x16x32_bf16 v[64:67], v[184:187], v[216:219], v[64:67]
	v_mfma_f32_16x16x32_bf16 v[116:119], v[180:183], v[196:199], v[116:119]
	v_mfma_f32_16x16x32_bf16 v[112:115], v[188:191], v[196:199], v[112:115]
	v_mfma_f32_16x16x32_bf16 v[100:103], v[180:183], v[204:207], v[100:103]
	v_mfma_f32_16x16x32_bf16 v[96:99], v[188:191], v[204:207], v[96:99]
	v_mfma_f32_16x16x32_bf16 v[84:87], v[180:183], v[212:215], v[84:87]
	v_mfma_f32_16x16x32_bf16 v[80:83], v[188:191], v[212:215], v[80:83]
	v_mfma_f32_16x16x32_bf16 v[68:71], v[180:183], v[240:243], v[68:71]
	v_mfma_f32_16x16x32_bf16 v[64:67], v[188:191], v[240:243], v[64:67]
	s_setprio 0
	s_barrier
	s_add_i32 s62, s33, s45
	v_lshl_add_u64 v[244:245], v[220:221], 0, v[168:169]
	s_mov_b32 m0, s62
	ds_read_b128 v[192:195], v151 offset:16384
	ds_read_b128 v[196:199], v151 offset:17408
	ds_read_b128 v[200:203], v151 offset:18432
	ds_read_b128 v[204:207], v151 offset:19456
	ds_read_b128 v[208:211], v151 offset:20480
	ds_read_b128 v[212:215], v151 offset:21504
	ds_read_b128 v[216:219], v151 offset:22528
	ds_read_b128 v[240:243], v151 offset:23552
	global_load_lds_dwordx4 v[244:245], off
	v_lshl_add_u64 v[246:247], v[220:221], 0, v[128:129]
	s_add_i32 m0, s62, 0x2000
	v_lshl_add_u64 v[220:221], v[220:221], 0, s[12:13]
	s_add_i32 s10, s10, s45
	global_load_lds_dwordx4 v[246:247], off
	v_lshl_add_u64 v[248:249], v[220:221], 0, v[168:169]
	s_mov_b32 m0, s10
	v_lshl_add_u64 v[220:221], v[220:221], 0, v[128:129]
	global_load_lds_dwordx4 v[248:249], off
	s_add_i32 m0, s10, 0x2000
	v_lshl_add_u64 v[250:251], v[146:147], 0, v[132:133]
	global_load_lds_dwordx4 v[220:221], off
	s_mov_b32 m0, s25
	v_lshl_add_u64 v[252:253], v[146:147], 0, v[130:131]
	global_load_lds_dwordx4 v[250:251], off
	s_mov_b32 m0, s50
	s_nop 0
	global_load_lds_dwordx4 v[252:253], off
	s_waitcnt vmcnt(8)
	s_waitcnt lgkmcnt(0)
	s_barrier
; #define PG8_STAGE(bufoff, gbase, voff) do { _Pragma("unroll") for (int _i = 0; _i < 2; ++_i) \
;         __builtin_amdgcn_global_load_lds((const unsigned*)((const char*)(gbase) + (voff)[_i]), (LAS unsigned*)(lds + (bufoff) + ldsw + _i * 8192), 16, 0, 0); } while (0)
; #define PG8_LDA(dst, b, h) do { _Pragma("unroll") for (int m = 0; m < 4; ++m) _Pragma("unroll") for (int k = 0; k < 2; ++k) dst[m][k] = *(const LAS bf16x8*)(lds + PG8_SA(b, h) + aoff + m * 2048 + k * 1024); } while (0)
; #define PG8_LDB(dst, b, h) do { _Pragma("unroll") for (int n = 0; n < 2; ++n) _Pragma("unroll") for (int k = 0; k < 2; ++k) dst[n][k] = *(const LAS bf16x8*)(lds + PG8_SB(b, h) + boff + n * 2048 + k * 1024); } while (0)
; #define PG8_MMA(ai, bj, At, Bt) do { __builtin_amdgcn_s_setprio(1); _Pragma("unroll") for (int k = 0; k < 2; ++k) _Pragma("unroll") for (int m = 0; m < 4; ++m) _Pragma("unroll") for (int n = 0; n < 2; ++n) \
;         acc[ai][bj][m][n] = __builtin_amdgcn_mfma_f32_16x16x32_bf16(Bt[n][k], At[m][k], acc[ai][bj][m][n], 0, 0, 0); __builtin_amdgcn_s_setprio(0); } while (0)
; #define PG8_WAIT_V(n) asm volatile("s_waitcnt vmcnt(" #n ")" ::: "memory")
; #define PG8_WAIT_L(n) asm volatile("s_waitcnt lgkmcnt(" #n ")" ::: "memory")
; #define PG8_BAR __builtin_amdgcn_s_barrier()
; #define PG8_SCHED __builtin_amdgcn_sched_barrier(0)
; template <class Epi, bool ALIGN_EPI>
; __device__ __forceinline__ void gemm_phase(LAS unsigned char* lds, const Gemm g, const StaticOrder& S, const Epi& E, const int tid) {
;     ...
;             PG8_WAIT_V(8); PG8_WAIT_L(0); PG8_BAR; PG8_MMA(1, 0, At, B0); PG8_MMA(1, 1, At, B1); PG8_BAR; PG8_SCHED;
;             PG8_LDB(B0, 1, 0); PG8_LDB(B1, 1, 1); PG8_SCHED; PG8_LDA(At, 1, 0); PG8_STAGE(PG8_SA(0, 1), a2 + hA, voffA);
;             PG8_WAIT_V(8); PG8_WAIT_L(0); PG8_BAR; PG8_MMA(0, 0, At, B0); PG8_MMA(0, 1, At, B1); PG8_BAR; PG8_SCHED;
	s_setprio 1
	s_waitcnt lgkmcnt(0)
	v_mfma_f32_16x16x32_bf16 v[60:63], v[152:155], v[192:195], v[60:63]
	v_mfma_f32_16x16x32_bf16 v[56:59], v[160:163], v[192:195], v[56:59]
	v_mfma_f32_16x16x32_bf16 v[44:47], v[152:155], v[200:203], v[44:47]
	v_mfma_f32_16x16x32_bf16 v[40:43], v[160:163], v[200:203], v[40:43]
	v_mfma_f32_16x16x32_bf16 v[28:31], v[152:155], v[208:211], v[28:31]
	v_mfma_f32_16x16x32_bf16 v[24:27], v[160:163], v[208:211], v[24:27]
	v_mfma_f32_16x16x32_bf16 v[12:15], v[152:155], v[216:219], v[12:15]
	v_mfma_f32_16x16x32_bf16 v[8:11], v[160:163], v[216:219], v[8:11]
	v_mfma_f32_16x16x32_bf16 v[60:63], v[156:159], v[196:199], v[60:63]
	v_mfma_f32_16x16x32_bf16 v[56:59], v[164:167], v[196:199], v[56:59]
	v_mfma_f32_16x16x32_bf16 v[44:47], v[156:159], v[204:207], v[44:47]
	v_mfma_f32_16x16x32_bf16 v[40:43], v[164:167], v[204:207], v[40:43]
	v_mfma_f32_16x16x32_bf16 v[28:31], v[156:159], v[212:215], v[28:31]
	v_mfma_f32_16x16x32_bf16 v[24:27], v[164:167], v[212:215], v[24:27]
	v_mfma_f32_16x16x32_bf16 v[12:15], v[156:159], v[240:243], v[12:15]
	v_mfma_f32_16x16x32_bf16 v[8:11], v[164:167], v[240:243], v[8:11]
	s_setprio 0
	s_setprio 1
	v_mfma_f32_16x16x32_bf16 v[52:55], v[176:179], v[192:195], v[52:55]
	v_mfma_f32_16x16x32_bf16 v[48:51], v[184:187], v[192:195], v[48:51]
	v_mfma_f32_16x16x32_bf16 v[36:39], v[176:179], v[200:203], v[36:39]
	v_mfma_f32_16x16x32_bf16 v[32:35], v[184:187], v[200:203], v[32:35]
	v_mfma_f32_16x16x32_bf16 v[20:23], v[176:179], v[208:211], v[20:23]
	v_mfma_f32_16x16x32_bf16 v[16:19], v[184:187], v[208:211], v[16:19]
	v_mfma_f32_16x16x32_bf16 v[4:7], v[176:179], v[216:219], v[4:7]
	v_mfma_f32_16x16x32_bf16 v[0:3], v[184:187], v[216:219], v[0:3]
	v_mfma_f32_16x16x32_bf16 v[52:55], v[180:183], v[196:199], v[52:55]
	v_mfma_f32_16x16x32_bf16 v[48:51], v[188:191], v[196:199], v[48:51]
	v_mfma_f32_16x16x32_bf16 v[36:39], v[180:183], v[204:207], v[36:39]
	v_mfma_f32_16x16x32_bf16 v[32:35], v[188:191], v[204:207], v[32:35]
	v_mfma_f32_16x16x32_bf16 v[20:23], v[180:183], v[212:215], v[20:23]
	v_mfma_f32_16x16x32_bf16 v[16:19], v[188:191], v[212:215], v[16:19]
	v_mfma_f32_16x16x32_bf16 v[4:7], v[180:183], v[240:243], v[4:7]
	v_mfma_f32_16x16x32_bf16 v[0:3], v[188:191], v[240:243], v[0:3]
	s_setprio 0
	s_barrier
	s_add_i32 s10, 0, 0x18000
	v_add_u32_e32 v148, s10, v149
	s_add_i32 s62, 0, 0x1c000
	ds_read_b128 v[152:155], v148
	ds_read_b128 v[156:159], v148 offset:1024
	ds_read_b128 v[160:163], v148 offset:2048
	ds_read_b128 v[164:167], v148 offset:3072
	v_add_u32_e32 v148, s62, v149
	ds_read_b128 v[176:179], v148
	ds_read_b128 v[180:183], v148 offset:1024
	ds_read_b128 v[184:187], v148 offset:2048
	ds_read_b128 v[188:191], v148 offset:3072
	v_lshl_add_u64 v[146:147], v[146:147], 0, s[94:95]
	s_mov_b32 m0, s51
	v_lshl_add_u64 v[226:227], v[146:147], 0, v[132:133]
	ds_read_b128 v[192:195], v151 offset:32768
	ds_read_b128 v[196:199], v151 offset:33792
	ds_read_b128 v[200:203], v151 offset:34816
	ds_read_b128 v[204:207], v151 offset:35840
	ds_read_b128 v[208:211], v151 offset:36864
	ds_read_b128 v[212:215], v151 offset:37888
	ds_read_b128 v[216:219], v151 offset:38912
	ds_read_b128 v[240:243], v151 offset:39936
	global_load_lds_dwordx4 v[226:227], off
	v_lshl_add_u64 v[146:147], v[146:147], 0, v[130:131]
	s_mov_b32 m0, s52
	s_nop 0
	global_load_lds_dwordx4 v[146:147], off
	s_waitcnt vmcnt(8)
	s_waitcnt lgkmcnt(0)
	s_barrier
	s_setprio 1
	s_waitcnt lgkmcnt(0)
	v_mfma_f32_16x16x32_bf16 v[124:127], v[152:155], v[192:195], v[124:127]
	v_mfma_f32_16x16x32_bf16 v[120:123], v[160:163], v[192:195], v[120:123]
	v_mfma_f32_16x16x32_bf16 v[108:111], v[152:155], v[200:203], v[108:111]
	v_mfma_f32_16x16x32_bf16 v[104:107], v[160:163], v[200:203], v[104:107]
	v_mfma_f32_16x16x32_bf16 v[92:95], v[152:155], v[208:211], v[92:95]
	v_mfma_f32_16x16x32_bf16 v[88:91], v[160:163], v[208:211], v[88:91]
	v_mfma_f32_16x16x32_bf16 v[76:79], v[152:155], v[216:219], v[76:79]
	v_mfma_f32_16x16x32_bf16 v[72:75], v[160:163], v[216:219], v[72:75]
	v_mfma_f32_16x16x32_bf16 v[124:127], v[156:159], v[196:199], v[124:127]
	v_mfma_f32_16x16x32_bf16 v[120:123], v[164:167], v[196:199], v[120:123]
	v_mfma_f32_16x16x32_bf16 v[108:111], v[156:159], v[204:207], v[108:111]
	v_mfma_f32_16x16x32_bf16 v[104:107], v[164:167], v[204:207], v[104:107]
	v_mfma_f32_16x16x32_bf16 v[92:95], v[156:159], v[212:215], v[92:95]
	v_mfma_f32_16x16x32_bf16 v[88:91], v[164:167], v[212:215], v[88:91]
	v_mfma_f32_16x16x32_bf16 v[76:79], v[156:159], v[240:243], v[76:79]
	v_mfma_f32_16x16x32_bf16 v[72:75], v[164:167], v[240:243], v[72:75]
	s_setprio 0
	s_setprio 1
	v_mfma_f32_16x16x32_bf16 v[116:119], v[176:179], v[192:195], v[116:119]
	v_mfma_f32_16x16x32_bf16 v[112:115], v[184:187], v[192:195], v[112:115]
	v_mfma_f32_16x16x32_bf16 v[100:103], v[176:179], v[200:203], v[100:103]
	v_mfma_f32_16x16x32_bf16 v[96:99], v[184:187], v[200:203], v[96:99]
	v_mfma_f32_16x16x32_bf16 v[84:87], v[176:179], v[208:211], v[84:87]
	v_mfma_f32_16x16x32_bf16 v[80:83], v[184:187], v[208:211], v[80:83]
	v_mfma_f32_16x16x32_bf16 v[68:71], v[176:179], v[216:219], v[68:71]
	v_mfma_f32_16x16x32_bf16 v[64:67], v[184:187], v[216:219], v[64:67]
	v_mfma_f32_16x16x32_bf16 v[116:119], v[180:183], v[196:199], v[116:119]
	v_mfma_f32_16x16x32_bf16 v[112:115], v[188:191], v[196:199], v[112:115]
	v_mfma_f32_16x16x32_bf16 v[100:103], v[180:183], v[204:207], v[100:103]
	v_mfma_f32_16x16x32_bf16 v[96:99], v[188:191], v[204:207], v[96:99]
	v_mfma_f32_16x16x32_bf16 v[84:87], v[180:183], v[212:215], v[84:87]
	v_mfma_f32_16x16x32_bf16 v[80:83], v[188:191], v[212:215], v[80:83]
	v_mfma_f32_16x16x32_bf16 v[68:71], v[180:183], v[240:243], v[68:71]
	v_mfma_f32_16x16x32_bf16 v[64:67], v[188:191], v[240:243], v[64:67]
	s_setprio 0
	s_barrier
; #define PG8_STAGE(bufoff, gbase, voff) do { _Pragma("unroll") for (int _i = 0; _i < 2; ++_i) \
;         __builtin_amdgcn_global_load_lds((const unsigned*)((const char*)(gbase) + (voff)[_i]), (LAS unsigned*)(lds + (bufoff) + ldsw + _i * 8192), 16, 0, 0); } while (0)
; #define PG8_LDA(dst, b, h) do { _Pragma("unroll") for (int m = 0; m < 4; ++m) _Pragma("unroll") for (int k = 0; k < 2; ++k) dst[m][k] = *(const LAS bf16x8*)(lds + PG8_SA(b, h) + aoff + m * 2048 + k * 1024); } while (0)
; #define PG8_MMA(ai, bj, At, Bt) do { __builtin_amdgcn_s_setprio(1); _Pragma("unroll") for (int k = 0; k < 2; ++k) _Pragma("unroll") for (int m = 0; m < 4; ++m) _Pragma("unroll") for (int n = 0; n < 2; ++n) \
;         acc[ai][bj][m][n] = __builtin_amdgcn_mfma_f32_16x16x32_bf16(Bt[n][k], At[m][k], acc[ai][bj][m][n], 0, 0, 0); __builtin_amdgcn_s_setprio(0); } while (0)
; #define PG8_WAIT_V(n) asm volatile("s_waitcnt vmcnt(" #n ")" ::: "memory")
; #define PG8_WAIT_L(n) asm volatile("s_waitcnt lgkmcnt(" #n ")" ::: "memory")
; #define PG8_BAR __builtin_amdgcn_s_barrier()
; #define PG8_SCHED __builtin_amdgcn_sched_barrier(0)
; template <class Epi, bool ALIGN_EPI>
; __device__ __forceinline__ void gemm_phase(LAS unsigned char* lds, const Gemm g, const StaticOrder& S, const Epi& E, const int tid) {
;     ...
;             PG8_LDA(At, 1, 1); PG8_STAGE(PG8_SB(1, 0), b3, voffB); PG8_STAGE(PG8_SB(1, 1), b3 + hB, voffB); PG8_STAGE(PG8_SA(1, 0), a3, voffA);
;             PG8_WAIT_V(8); PG8_WAIT_L(0); PG8_BAR; PG8_MMA(1, 0, At, B0); PG8_MMA(1, 1, At, B1); PG8_BAR; PG8_SCHED;
	s_add_i32 s10, s10, s45
	v_lshl_add_u64 v[146:147], v[244:245], 0, s[92:93]
	s_mov_b32 m0, s10
	ds_read_b128 v[192:195], v151 offset:49152
	ds_read_b128 v[196:199], v151 offset:50176
	ds_read_b128 v[200:203], v151 offset:51200
	ds_read_b128 v[204:207], v151 offset:52224
	ds_read_b128 v[208:211], v151 offset:53248
	ds_read_b128 v[212:215], v151 offset:54272
	ds_read_b128 v[216:219], v151 offset:55296
	ds_read_b128 v[240:243], v151 offset:56320
	global_load_lds_dwordx4 v[146:147], off
	v_lshl_add_u64 v[146:147], v[246:247], 0, s[92:93]
	s_add_i32 m0, s10, 0x2000
	s_add_i32 s10, s62, s45
	global_load_lds_dwordx4 v[146:147], off
	v_lshl_add_u64 v[146:147], v[248:249], 0, s[92:93]
	s_mov_b32 m0, s10
	s_nop 0
	global_load_lds_dwordx4 v[146:147], off
	v_lshl_add_u64 v[146:147], v[220:221], 0, s[92:93]
	s_add_i32 m0, s10, 0x2000
	s_nop 0
	global_load_lds_dwordx4 v[146:147], off
	v_lshl_add_u64 v[146:147], v[250:251], 0, s[92:93]
	s_mov_b32 m0, s53
	s_nop 0
	global_load_lds_dwordx4 v[146:147], off
	v_lshl_add_u64 v[146:147], v[252:253], 0, s[92:93]
	s_mov_b32 m0, s54
	s_nop 0
	global_load_lds_dwordx4 v[146:147], off
	s_waitcnt vmcnt(8)
	s_waitcnt lgkmcnt(0)
	s_barrier
	s_waitcnt lgkmcnt(0)
; __device__ __forceinline__ unsigned cvt_pk_bf16(float lo, float hi) { unsigned r; asm volatile("v_cvt_pk_bf16_f32 %0, %1, %2" : "=v"(r) : "v"(lo), "v"(hi)); return r; }
; __device__ __forceinline__ float gelu_tanh(float x) { const float u = 0.7978845608028654f * (x + 0.044715f * x * x * x); return x * fast_rcp(1.0f + fast_exp2(-2.0f * LOG2E * u)); }
;     __device__ __forceinline__ void operator()(const f32x4 (&acc)[2][2][4][2], const Unit& u, int wr, int wc, int fr, int fq) const {
;         const int row0 = u.pm * BM + wr * 64 + fr, col0 = u.pn * BM + wc * 32 + 8 * fq;
;         float rsv[2][4]; load_rstd(rsv, ssq, row0);
; #pragma unroll
;         for (int ai = 0; ai < 2; ++ai)
; #pragma unroll
;             for (int m = 0; m < 4; ++m) { const int row = row0 + ai * HALF + m * 16; bf16_t* rowp = O + (size_t)row * ldc + col0; const float rs = rsv[ai][m];
; #pragma unroll
;                 for (int bj = 0; bj < 2; ++bj) { f32x4 v0 = acc[ai][bj][m][0] * rs, v1 = acc[ai][bj][m][1] * rs;
;                     if (ACT == 1) {
; #pragma unroll
;                         for (int j = 0; j < 4; ++j) { v0[j] = gelu_tanh(v0[j]); v1[j] = gelu_tanh(v1[j]); } }
;                     u32x4 w; w.x = cvt_pk_bf16(v0[0], v0[1]); w.y = cvt_pk_bf16(v0[2], v0[3]); w.z = cvt_pk_bf16(v1[0], v1[1]); w.w = cvt_pk_bf16(v1[2], v1[3]);
;                     *(u32x4*)(rowp + bj * HALF) = w; } }
; template <class Epi, bool ALIGN_EPI>
; __device__ __forceinline__ void gemm_phase(LAS unsigned char* lds, const Gemm g, const StaticOrder& S, const Epi& E, const int tid) {
;     ...
;             PG8_WAIT_V(8); PG8_WAIT_L(0); PG8_BAR; PG8_MMA(1, 0, At, B0); PG8_MMA(1, 1, At, B1); PG8_BAR; PG8_SCHED;
;         }
;         if constexpr (ALIGN_EPI) { if (wr == 0) PG8_BAR; }
;         { int t2 = tid; asm volatile("" : "+v"(t2)); const int l2 = t2 & 63, w2 = __builtin_amdgcn_readfirstlane(t2 >> 6); E(acc, cur, w2 >> 2, w2 & 3, l2 & 15, l2 >> 4); }
;         if (!has_next) break;
; #pragma unroll
;         for (int a = 0; a < 2; ++a)
; #pragma unroll
;             for (int b = 0; b < 2; ++b)
; #pragma unroll
;                 for (int m = 0; m < 4; ++m)
; #pragma unroll
;                     for (int n = 0; n < 2; ++n) acc[a][b][m][n] = (f32x4){0.f, 0.f, 0.f, 0.f};
;         cur = nxt; cA = nA; cB = nB; ++ui;
;         if constexpr (ALIGN_EPI) { if (wr == 1) PG8_BAR; }
	v_mfma_f32_16x16x32_bf16 v[60:63], v[152:155], v[192:195], v[60:63]
	v_lshrrev_b32_e32 v171, 8, v170
	v_and_b32_e32 v234, 15, v170
	v_lshl_add_u32 v171, v171, 6, v234
	s_lshl_b32 s98, s61, 8
	v_add_u32_e32 v171, s98, v171
	v_mfma_f32_16x16x32_bf16 v[56:59], v[160:163], v[192:195], v[56:59]
	v_mul_lo_u32 v171, v171, s28
	v_bfe_u32 v234, v170, 6, 2
	v_bfe_u32 v224, v170, 4, 2
	v_lshlrev_b32_e32 v234, 5, v234
	v_lshl_or_b32 v234, v224, 3, v234
	v_mfma_f32_16x16x32_bf16 v[44:47], v[152:155], v[200:203], v[44:47]
	s_lshl_b32 s98, s60, 8
	v_add_u32_e32 v234, s98, v234
	v_add_lshl_u32 v232, v171, v234, 1
	v_mov_b32_e32 v233, 0
	v_lshl_add_u64 v[232:233], v[232:233], 0, s[30:31]
	v_mfma_f32_16x16x32_bf16 v[40:43], v[160:163], v[200:203], v[40:43]
	s_lshl_b32 s98, s28, 5
	s_mov_b32 s99, 0
	v_mul_f32_e32 v124, v172, v124
	v_mul_f32_e32 v125, v172, v125
	v_mul_f32_e32 v126, v172, v126
	v_mfma_f32_16x16x32_bf16 v[28:31], v[152:155], v[208:211], v[28:31]
	v_mul_f32_e32 v127, v172, v127
	v_mul_f32_e32 v120, v172, v120
	v_mul_f32_e32 v121, v172, v121
	v_mul_f32_e32 v122, v172, v122
	v_mul_f32_e32 v123, v172, v123
	v_mfma_f32_16x16x32_bf16 v[24:27], v[160:163], v[208:211], v[24:27]
	v_cvt_pk_bf16_f32 v124, v124, v125
	v_cvt_pk_bf16_f32 v125, v126, v127
	v_cvt_pk_bf16_f32 v126, v120, v121
	v_cvt_pk_bf16_f32 v127, v122, v123
	global_store_dwordx4 v[232:233], v[124:127], off
	v_mfma_f32_16x16x32_bf16 v[12:15], v[152:155], v[216:219], v[12:15]
	v_mul_f32_e32 v116, v172, v116
	v_mul_f32_e32 v117, v172, v117
	v_mul_f32_e32 v118, v172, v118
	v_mul_f32_e32 v119, v172, v119
	v_mul_f32_e32 v112, v172, v112
	v_mfma_f32_16x16x32_bf16 v[8:11], v[160:163], v[216:219], v[8:11]
	v_mul_f32_e32 v113, v172, v113
	v_mul_f32_e32 v114, v172, v114
	v_mul_f32_e32 v115, v172, v115
	v_cvt_pk_bf16_f32 v116, v116, v117
	v_cvt_pk_bf16_f32 v117, v118, v119
	v_mfma_f32_16x16x32_bf16 v[60:63], v[156:159], v[196:199], v[60:63]
	v_cvt_pk_bf16_f32 v118, v112, v113
	v_cvt_pk_bf16_f32 v119, v114, v115
	global_store_dwordx4 v[232:233], v[116:119], off offset:256
	v_lshl_add_u64 v[232:233], v[232:233], 0, s[98:99]
	v_mul_f32_e32 v108, v173, v108
	v_mfma_f32_16x16x32_bf16 v[56:59], v[164:167], v[196:199], v[56:59]
	v_mul_f32_e32 v109, v173, v109
	v_mul_f32_e32 v110, v173, v110
	v_mul_f32_e32 v111, v173, v111
	v_mul_f32_e32 v104, v173, v104
	v_mul_f32_e32 v105, v173, v105
	v_mfma_f32_16x16x32_bf16 v[44:47], v[156:159], v[204:207], v[44:47]
	v_mul_f32_e32 v106, v173, v106
	v_mul_f32_e32 v107, v173, v107
	v_cvt_pk_bf16_f32 v108, v108, v109
	v_cvt_pk_bf16_f32 v109, v110, v111
	v_cvt_pk_bf16_f32 v110, v104, v105
	v_mfma_f32_16x16x32_bf16 v[40:43], v[164:167], v[204:207], v[40:43]
	v_cvt_pk_bf16_f32 v111, v106, v107
	global_store_dwordx4 v[232:233], v[108:111], off
	v_mul_f32_e32 v100, v173, v100
	v_mul_f32_e32 v101, v173, v101
	v_mul_f32_e32 v102, v173, v102
	v_mfma_f32_16x16x32_bf16 v[28:31], v[156:159], v[212:215], v[28:31]
	v_mul_f32_e32 v103, v173, v103
	v_mul_f32_e32 v96, v173, v96
	v_mul_f32_e32 v97, v173, v97
	v_mul_f32_e32 v98, v173, v98
	v_mul_f32_e32 v99, v173, v99
	v_mfma_f32_16x16x32_bf16 v[24:27], v[164:167], v[212:215], v[24:27]
	v_cvt_pk_bf16_f32 v100, v100, v101
	v_cvt_pk_bf16_f32 v101, v102, v103
	v_cvt_pk_bf16_f32 v102, v96, v97
	v_cvt_pk_bf16_f32 v103, v98, v99
	global_store_dwordx4 v[232:233], v[100:103], off offset:256
	v_mfma_f32_16x16x32_bf16 v[12:15], v[156:159], v[240:243], v[12:15]
	v_lshl_add_u64 v[232:233], v[232:233], 0, s[98:99]
	v_mul_f32_e32 v92, v236, v92
	v_mul_f32_e32 v93, v236, v93
	v_mul_f32_e32 v94, v236, v94
	v_mul_f32_e32 v95, v236, v95
	v_mfma_f32_16x16x32_bf16 v[8:11], v[164:167], v[240:243], v[8:11]
	v_mul_f32_e32 v88, v236, v88
	v_mul_f32_e32 v89, v236, v89
	v_mul_f32_e32 v90, v236, v90
	v_mul_f32_e32 v91, v236, v91
	v_cvt_pk_bf16_f32 v92, v92, v93
	s_setprio 0
	v_mfma_f32_16x16x32_bf16 v[52:55], v[176:179], v[192:195], v[52:55]
	v_cvt_pk_bf16_f32 v93, v94, v95
	v_cvt_pk_bf16_f32 v94, v88, v89
	v_cvt_pk_bf16_f32 v95, v90, v91
	global_store_dwordx4 v[232:233], v[92:95], off
	v_mul_f32_e32 v84, v236, v84
	v_mfma_f32_16x16x32_bf16 v[48:51], v[184:187], v[192:195], v[48:51]
	v_mul_f32_e32 v85, v236, v85
	v_mul_f32_e32 v86, v236, v86
	v_mul_f32_e32 v87, v236, v87
	v_mul_f32_e32 v80, v236, v80
	v_mul_f32_e32 v81, v236, v81
	v_mfma_f32_16x16x32_bf16 v[36:39], v[176:179], v[200:203], v[36:39]
	v_mul_f32_e32 v82, v236, v82
	v_mul_f32_e32 v83, v236, v83
	v_cvt_pk_bf16_f32 v84, v84, v85
	v_cvt_pk_bf16_f32 v85, v86, v87
	v_cvt_pk_bf16_f32 v86, v80, v81
	v_mfma_f32_16x16x32_bf16 v[32:35], v[184:187], v[200:203], v[32:35]
	v_cvt_pk_bf16_f32 v87, v82, v83
	global_store_dwordx4 v[232:233], v[84:87], off offset:256
	v_lshl_add_u64 v[232:233], v[232:233], 0, s[98:99]
	v_mul_f32_e32 v76, v237, v76
	v_mul_f32_e32 v77, v237, v77
	v_mfma_f32_16x16x32_bf16 v[20:23], v[176:179], v[208:211], v[20:23]
	v_mul_f32_e32 v78, v237, v78
	v_mul_f32_e32 v79, v237, v79
	v_mul_f32_e32 v72, v237, v72
	v_mul_f32_e32 v73, v237, v73
	v_mul_f32_e32 v74, v237, v74
	v_mfma_f32_16x16x32_bf16 v[16:19], v[184:187], v[208:211], v[16:19]
	v_mul_f32_e32 v75, v237, v75
	v_cvt_pk_bf16_f32 v76, v76, v77
	v_cvt_pk_bf16_f32 v77, v78, v79
	v_cvt_pk_bf16_f32 v78, v72, v73
	v_cvt_pk_bf16_f32 v79, v74, v75
	v_mfma_f32_16x16x32_bf16 v[4:7], v[176:179], v[216:219], v[4:7]
	global_store_dwordx4 v[232:233], v[76:79], off
	v_mul_f32_e32 v68, v237, v68
	v_mul_f32_e32 v69, v237, v69
	v_mul_f32_e32 v70, v237, v70
	v_mul_f32_e32 v71, v237, v71
	v_mfma_f32_16x16x32_bf16 v[0:3], v[184:187], v[216:219], v[0:3]
	v_mul_f32_e32 v64, v237, v64
	v_mul_f32_e32 v65, v237, v65
	v_mul_f32_e32 v66, v237, v66
	v_mul_f32_e32 v67, v237, v67
	v_cvt_pk_bf16_f32 v68, v68, v69
	v_mfma_f32_16x16x32_bf16 v[52:55], v[180:183], v[196:199], v[52:55]
	v_cvt_pk_bf16_f32 v69, v70, v71
	v_cvt_pk_bf16_f32 v70, v64, v65
	v_cvt_pk_bf16_f32 v71, v66, v67
	global_store_dwordx4 v[232:233], v[68:71], off offset:256
	v_lshl_add_u64 v[232:233], v[232:233], 0, s[98:99]
	v_mfma_f32_16x16x32_bf16 v[48:51], v[188:191], v[196:199], v[48:51]
	v_lshl_add_u64 v[232:233], v[232:233], 0, s[98:99]
	v_lshl_add_u64 v[232:233], v[232:233], 0, s[98:99]
	v_lshl_add_u64 v[232:233], v[232:233], 0, s[98:99]
	v_lshl_add_u64 v[232:233], v[232:233], 0, s[98:99]
	v_mfma_f32_16x16x32_bf16 v[36:39], v[180:183], v[204:207], v[36:39]
	v_mfma_f32_16x16x32_bf16 v[32:35], v[188:191], v[204:207], v[32:35]
	v_mfma_f32_16x16x32_bf16 v[20:23], v[180:183], v[212:215], v[20:23]
	v_mfma_f32_16x16x32_bf16 v[16:19], v[188:191], v[212:215], v[16:19]
	v_mfma_f32_16x16x32_bf16 v[4:7], v[180:183], v[240:243], v[4:7]
	v_mfma_f32_16x16x32_bf16 v[0:3], v[188:191], v[240:243], v[0:3]
	s_setprio 0
	s_barrier
	v_lshl_add_u64 v[142:143], v[142:143], 0, s[80:81]
	v_lshl_add_u64 v[144:145], v[144:145], 0, s[80:81]
	s_and_b64 vcc, exec, s[8:9]
	s_cbranch_vccnz .Lq5_notdefer
	s_cmp_lg_u32 s59, s61
	s_cbranch_scc1 .Lq5_notdefer
	s_mov_b32 s101, 1
	s_mov_b32 s60, s58
	s_mov_b32 s61, s59
	v_mov_b64_e32 v[144:145], v[140:141]
	v_mov_b64_e32 v[142:143], v[138:139]
	s_branch .LBB0_346
